# also: lora2 tile epilogue by hand (bias once per tile, 16-byte stores, reciprocal by v_rcp_f32 + Newton step)
# speedup vs baseline: 1.0508x; 1.0109x over previous
.LBB0_904:
	s_or_b64 exec, exec, s[0:1]
	s_cmpk_gt_i32 s2, 0x207
	s_cbranch_scc1 .LBB0_1055
	s_mov_b32 s3, 0xfb588c0
	s_mov_b32 s13, 0x908000
	v_mov_b32_e32 v1, 0
	s_add_i32 s34, 0, 0x10000
	s_add_i32 s35, 0, 0x14000
	s_movk_i32 s38, 0x4080
	s_mov_b32 s12, 0x3f1b4598
	s_mov_b32 s39, s2
	s_branch .LBB0_908
.LBB0_907:
	s_or_b64 exec, exec, s[10:11]
	s_add_i32 s39, s39, s86
	s_cmpk_lt_i32 s39, 0x208
	s_cbranch_scc0 .LBB0_1055

.LBB0_912:
	s_waitcnt vmcnt(0)
	v_lshlrev_b32_e32 v0, 2, v166
	s_waitcnt lgkmcnt(0)
	s_barrier
	s_waitcnt lgkmcnt(0)
	v_lshl_or_b32 v137, s16, 7, v167
	v_lshl_or_b32 v0, s9, 6, v0
	s_and_b64 s[0:1], s[4:5], exec
	v_add_u32_e32 v130, s40, v137
	v_or_b32_e32 v136, s8, v0
	s_cselect_b32 s15, s73, s79
	s_cselect_b32 s14, s72, s78
	v_lshlrev_b32_e32 v0, 2, v136
	global_load_dwordx4 v[210:213], v0, s[14:15] offset:0
	global_load_dwordx4 v[214:217], v0, s[14:15] offset:64
	global_load_dwordx4 v[218:221], v0, s[14:15] offset:128
	global_load_dwordx4 v[222:225], v0, s[14:15] offset:192
	s_and_b64 s[0:1], s[4:5], exec
	s_mov_b32 s0, 0xdb188c0
	s_cselect_b32 s0, 0xbad88c0, s0
	s_add_u32 s0, s84, s0
	s_addc_u32 s1, s85, 0
	v_mov_b32_e32 v206, v130
	v_ashrrev_i32_e32 v207, 31, v130
	v_mov_b32_e32 v204, v130
	v_mov_b32_e32 v205, v207
	v_lshlrev_b64 v[204:205], 11, v[204:205]
	v_lshl_add_u64 v[204:205], s[0:1], 0, v[204:205]
	v_lshlrev_b32_e32 v207, 1, v136
	v_and_b32_e32 v226, 1, v166
	v_mul_u32_u24_e32 v226, 24, v226
	v_add_u32_e32 v208, v207, v226
	v_mov_b32_e32 v209, 0
	v_lshl_add_u64 v[204:205], v[204:205], 0, v[208:209]
	v_mov_b32_e32 v208, 0x8000
	s_cmp_eq_u64 s[4:5], 0
	s_waitcnt vmcnt(0)
	s_cbranch_scc1 .Ll2e_bf16
	v_add_f32_e32 v126, v126, v210
	v_add_f32_e32 v127, v127, v211
	v_add_f32_e32 v128, v128, v212
	v_add_f32_e32 v129, v129, v213
	v_mul_f32_e32 v126, 0xbfb8aa3b, v126
	v_mul_f32_e32 v127, 0xbfb8aa3b, v127
	v_mul_f32_e32 v128, 0xbfb8aa3b, v128
	v_mul_f32_e32 v129, 0xbfb8aa3b, v129
	v_exp_f32_e32 v126, v126
	v_exp_f32_e32 v127, v127
	v_exp_f32_e32 v128, v128
	v_exp_f32_e32 v129, v129
	s_nop 0
	v_add_f32_e32 v126, 1.0, v126
	v_add_f32_e32 v127, 1.0, v127
	v_add_f32_e32 v128, 1.0, v128
	v_add_f32_e32 v129, 1.0, v129
	v_rcp_f32_e32 v226, v126
	v_rcp_f32_e32 v227, v127
	v_rcp_f32_e32 v228, v128
	v_rcp_f32_e32 v229, v129
	s_nop 0
	v_fma_f32 v126, -v126, v226, 1.0
	v_fma_f32 v127, -v127, v227, 1.0
	v_fma_f32 v128, -v128, v228, 1.0
	v_fma_f32 v129, -v129, v229, 1.0
	v_fma_f32 v126, v126, v226, v226
	v_fma_f32 v127, v127, v227, v227
	v_fma_f32 v128, v128, v228, v228
	v_fma_f32 v129, v129, v229, v229
	v_mul_f32_e32 v126, s12, v126
	v_mul_f32_e32 v127, s12, v127
	v_mul_f32_e32 v128, s12, v128
	v_mul_f32_e32 v129, s12, v129
	v_add_f32_e32 v122, v122, v214
	v_add_f32_e32 v123, v123, v215
	v_add_f32_e32 v124, v124, v216
	v_add_f32_e32 v125, v125, v217
	v_mul_f32_e32 v122, 0xbfb8aa3b, v122
	v_mul_f32_e32 v123, 0xbfb8aa3b, v123
	v_mul_f32_e32 v124, 0xbfb8aa3b, v124
	v_mul_f32_e32 v125, 0xbfb8aa3b, v125
	v_exp_f32_e32 v122, v122
	v_exp_f32_e32 v123, v123
	v_exp_f32_e32 v124, v124
	v_exp_f32_e32 v125, v125
	s_nop 0
	v_add_f32_e32 v122, 1.0, v122
	v_add_f32_e32 v123, 1.0, v123
	v_add_f32_e32 v124, 1.0, v124
	v_add_f32_e32 v125, 1.0, v125
	v_rcp_f32_e32 v226, v122
	v_rcp_f32_e32 v227, v123
	v_rcp_f32_e32 v228, v124
	v_rcp_f32_e32 v229, v125
	s_nop 0
	v_fma_f32 v122, -v122, v226, 1.0
	v_fma_f32 v123, -v123, v227, 1.0
	v_fma_f32 v124, -v124, v228, 1.0
	v_fma_f32 v125, -v125, v229, 1.0
	v_fma_f32 v122, v122, v226, v226
	v_fma_f32 v123, v123, v227, v227
	v_fma_f32 v124, v124, v228, v228
	v_fma_f32 v125, v125, v229, v229
	v_mul_f32_e32 v122, s12, v122
	v_mul_f32_e32 v123, s12, v123
	v_mul_f32_e32 v124, s12, v124
	v_mul_f32_e32 v125, s12, v125
	v_add_f32_e32 v118, v118, v218
	v_add_f32_e32 v119, v119, v219
	v_add_f32_e32 v120, v120, v220
	v_add_f32_e32 v121, v121, v221
	v_mul_f32_e32 v118, 0xbfb8aa3b, v118
	v_mul_f32_e32 v119, 0xbfb8aa3b, v119
	v_mul_f32_e32 v120, 0xbfb8aa3b, v120
	v_mul_f32_e32 v121, 0xbfb8aa3b, v121
	v_exp_f32_e32 v118, v118
	v_exp_f32_e32 v119, v119
	v_exp_f32_e32 v120, v120
	v_exp_f32_e32 v121, v121
	s_nop 0
	v_add_f32_e32 v118, 1.0, v118
	v_add_f32_e32 v119, 1.0, v119
	v_add_f32_e32 v120, 1.0, v120
	v_add_f32_e32 v121, 1.0, v121
	v_rcp_f32_e32 v226, v118
	v_rcp_f32_e32 v227, v119
	v_rcp_f32_e32 v228, v120
	v_rcp_f32_e32 v229, v121
	s_nop 0
	v_fma_f32 v118, -v118, v226, 1.0
	v_fma_f32 v119, -v119, v227, 1.0
	v_fma_f32 v120, -v120, v228, 1.0
	v_fma_f32 v121, -v121, v229, 1.0
	v_fma_f32 v118, v118, v226, v226
	v_fma_f32 v119, v119, v227, v227
	v_fma_f32 v120, v120, v228, v228
	v_fma_f32 v121, v121, v229, v229
	v_mul_f32_e32 v118, s12, v118
	v_mul_f32_e32 v119, s12, v119
	v_mul_f32_e32 v120, s12, v120
	v_mul_f32_e32 v121, s12, v121
	v_add_f32_e32 v114, v114, v222
	v_add_f32_e32 v115, v115, v223
	v_add_f32_e32 v116, v116, v224
	v_add_f32_e32 v117, v117, v225
	v_mul_f32_e32 v114, 0xbfb8aa3b, v114
	v_mul_f32_e32 v115, 0xbfb8aa3b, v115
	v_mul_f32_e32 v116, 0xbfb8aa3b, v116
	v_mul_f32_e32 v117, 0xbfb8aa3b, v117
	v_exp_f32_e32 v114, v114
	v_exp_f32_e32 v115, v115
	v_exp_f32_e32 v116, v116
	v_exp_f32_e32 v117, v117
	s_nop 0
	v_add_f32_e32 v114, 1.0, v114
	v_add_f32_e32 v115, 1.0, v115
	v_add_f32_e32 v116, 1.0, v116
	v_add_f32_e32 v117, 1.0, v117
	v_rcp_f32_e32 v226, v114
	v_rcp_f32_e32 v227, v115
	v_rcp_f32_e32 v228, v116
	v_rcp_f32_e32 v229, v117
	s_nop 0
	v_fma_f32 v114, -v114, v226, 1.0
	v_fma_f32 v115, -v115, v227, 1.0
	v_fma_f32 v116, -v116, v228, 1.0
	v_fma_f32 v117, -v117, v229, 1.0
	v_fma_f32 v114, v114, v226, v226
	v_fma_f32 v115, v115, v227, v227
	v_fma_f32 v116, v116, v228, v228
	v_fma_f32 v117, v117, v229, v229
	v_mul_f32_e32 v114, s12, v114
	v_mul_f32_e32 v115, s12, v115
	v_mul_f32_e32 v116, s12, v116
	v_mul_f32_e32 v117, s12, v117
	v_cvt_pk_f16_f32 v196, v126, v127
	v_cvt_pk_f16_f32 v197, v128, v129
	v_cvt_pk_f16_f32 v198, v122, v123
	v_cvt_pk_f16_f32 v199, v124, v125
	v_cvt_pk_f16_f32 v200, v118, v119
	v_cvt_pk_f16_f32 v201, v120, v121
	v_cvt_pk_f16_f32 v202, v114, v115
	v_cvt_pk_f16_f32 v203, v116, v117
	v_cmp_gt_i32_e32 vcc, s38, v206
	s_nop 0
	v_permlane16_swap_b32_e32 v196, v198
	v_permlane16_swap_b32_e32 v197, v199
	v_permlane16_swap_b32_e32 v200, v202
	v_permlane16_swap_b32_e32 v201, v203
	s_and_saveexec_b64 s[0:1], vcc
	global_store_dwordx4 v[204:205], v[196:199], off
	global_store_dwordx4 v[204:205], v[200:203], off offset:64
	s_or_b64 exec, exec, s[0:1]
	v_lshl_add_u64 v[204:205], v[204:205], 0, v[208:209]
	v_add_u32_e32 v206, 16, v206
	v_add_f32_e32 v110, v110, v210
	v_add_f32_e32 v111, v111, v211
	v_add_f32_e32 v112, v112, v212
	v_add_f32_e32 v113, v113, v213
	v_mul_f32_e32 v110, 0xbfb8aa3b, v110
	v_mul_f32_e32 v111, 0xbfb8aa3b, v111
	v_mul_f32_e32 v112, 0xbfb8aa3b, v112
	v_mul_f32_e32 v113, 0xbfb8aa3b, v113
	v_exp_f32_e32 v110, v110
	v_exp_f32_e32 v111, v111
	v_exp_f32_e32 v112, v112
	v_exp_f32_e32 v113, v113
	s_nop 0
	v_add_f32_e32 v110, 1.0, v110
	v_add_f32_e32 v111, 1.0, v111
	v_add_f32_e32 v112, 1.0, v112
	v_add_f32_e32 v113, 1.0, v113
	v_rcp_f32_e32 v226, v110
	v_rcp_f32_e32 v227, v111
	v_rcp_f32_e32 v228, v112
	v_rcp_f32_e32 v229, v113
	s_nop 0
	v_fma_f32 v110, -v110, v226, 1.0
	v_fma_f32 v111, -v111, v227, 1.0
	v_fma_f32 v112, -v112, v228, 1.0
	v_fma_f32 v113, -v113, v229, 1.0
	v_fma_f32 v110, v110, v226, v226
	v_fma_f32 v111, v111, v227, v227
	v_fma_f32 v112, v112, v228, v228
	v_fma_f32 v113, v113, v229, v229
	v_mul_f32_e32 v110, s12, v110
	v_mul_f32_e32 v111, s12, v111
	v_mul_f32_e32 v112, s12, v112
	v_mul_f32_e32 v113, s12, v113
	v_add_f32_e32 v106, v106, v214
	v_add_f32_e32 v107, v107, v215
	v_add_f32_e32 v108, v108, v216
	v_add_f32_e32 v109, v109, v217
	v_mul_f32_e32 v106, 0xbfb8aa3b, v106
	v_mul_f32_e32 v107, 0xbfb8aa3b, v107
	v_mul_f32_e32 v108, 0xbfb8aa3b, v108
	v_mul_f32_e32 v109, 0xbfb8aa3b, v109
	v_exp_f32_e32 v106, v106
	v_exp_f32_e32 v107, v107
	v_exp_f32_e32 v108, v108
	v_exp_f32_e32 v109, v109
	s_nop 0
	v_add_f32_e32 v106, 1.0, v106
	v_add_f32_e32 v107, 1.0, v107
	v_add_f32_e32 v108, 1.0, v108
	v_add_f32_e32 v109, 1.0, v109
	v_rcp_f32_e32 v226, v106
	v_rcp_f32_e32 v227, v107
	v_rcp_f32_e32 v228, v108
	v_rcp_f32_e32 v229, v109
	s_nop 0
	v_fma_f32 v106, -v106, v226, 1.0
	v_fma_f32 v107, -v107, v227, 1.0
	v_fma_f32 v108, -v108, v228, 1.0
	v_fma_f32 v109, -v109, v229, 1.0
	v_fma_f32 v106, v106, v226, v226
	v_fma_f32 v107, v107, v227, v227
	v_fma_f32 v108, v108, v228, v228
	v_fma_f32 v109, v109, v229, v229
	v_mul_f32_e32 v106, s12, v106
	v_mul_f32_e32 v107, s12, v107
	v_mul_f32_e32 v108, s12, v108
	v_mul_f32_e32 v109, s12, v109
	v_add_f32_e32 v102, v102, v218
	v_add_f32_e32 v103, v103, v219
	v_add_f32_e32 v104, v104, v220
	v_add_f32_e32 v105, v105, v221
	v_mul_f32_e32 v102, 0xbfb8aa3b, v102
	v_mul_f32_e32 v103, 0xbfb8aa3b, v103
	v_mul_f32_e32 v104, 0xbfb8aa3b, v104
	v_mul_f32_e32 v105, 0xbfb8aa3b, v105
	v_exp_f32_e32 v102, v102
	v_exp_f32_e32 v103, v103
	v_exp_f32_e32 v104, v104
	v_exp_f32_e32 v105, v105
	s_nop 0
	v_add_f32_e32 v102, 1.0, v102
	v_add_f32_e32 v103, 1.0, v103
	v_add_f32_e32 v104, 1.0, v104
	v_add_f32_e32 v105, 1.0, v105
	v_rcp_f32_e32 v226, v102
	v_rcp_f32_e32 v227, v103
	v_rcp_f32_e32 v228, v104
	v_rcp_f32_e32 v229, v105
	s_nop 0
	v_fma_f32 v102, -v102, v226, 1.0
	v_fma_f32 v103, -v103, v227, 1.0
	v_fma_f32 v104, -v104, v228, 1.0
	v_fma_f32 v105, -v105, v229, 1.0
	v_fma_f32 v102, v102, v226, v226
	v_fma_f32 v103, v103, v227, v227
	v_fma_f32 v104, v104, v228, v228
	v_fma_f32 v105, v105, v229, v229
	v_mul_f32_e32 v102, s12, v102
	v_mul_f32_e32 v103, s12, v103
	v_mul_f32_e32 v104, s12, v104
	v_mul_f32_e32 v105, s12, v105
	v_add_f32_e32 v98, v98, v222
	v_add_f32_e32 v99, v99, v223
	v_add_f32_e32 v100, v100, v224
	v_add_f32_e32 v101, v101, v225
	v_mul_f32_e32 v98, 0xbfb8aa3b, v98
	v_mul_f32_e32 v99, 0xbfb8aa3b, v99
	v_mul_f32_e32 v100, 0xbfb8aa3b, v100
	v_mul_f32_e32 v101, 0xbfb8aa3b, v101
	v_exp_f32_e32 v98, v98
	v_exp_f32_e32 v99, v99
	v_exp_f32_e32 v100, v100
	v_exp_f32_e32 v101, v101
	s_nop 0
	v_add_f32_e32 v98, 1.0, v98
	v_add_f32_e32 v99, 1.0, v99
	v_add_f32_e32 v100, 1.0, v100
	v_add_f32_e32 v101, 1.0, v101
	v_rcp_f32_e32 v226, v98
	v_rcp_f32_e32 v227, v99
	v_rcp_f32_e32 v228, v100
	v_rcp_f32_e32 v229, v101
	s_nop 0
	v_fma_f32 v98, -v98, v226, 1.0
	v_fma_f32 v99, -v99, v227, 1.0
	v_fma_f32 v100, -v100, v228, 1.0
	v_fma_f32 v101, -v101, v229, 1.0
	v_fma_f32 v98, v98, v226, v226
	v_fma_f32 v99, v99, v227, v227
	v_fma_f32 v100, v100, v228, v228
	v_fma_f32 v101, v101, v229, v229
	v_mul_f32_e32 v98, s12, v98
	v_mul_f32_e32 v99, s12, v99
	v_mul_f32_e32 v100, s12, v100
	v_mul_f32_e32 v101, s12, v101
	v_cvt_pk_f16_f32 v196, v110, v111
	v_cvt_pk_f16_f32 v197, v112, v113
	v_cvt_pk_f16_f32 v198, v106, v107
	v_cvt_pk_f16_f32 v199, v108, v109
	v_cvt_pk_f16_f32 v200, v102, v103
	v_cvt_pk_f16_f32 v201, v104, v105
	v_cvt_pk_f16_f32 v202, v98, v99
	v_cvt_pk_f16_f32 v203, v100, v101
	v_cmp_gt_i32_e32 vcc, s38, v206
	s_nop 0
	v_permlane16_swap_b32_e32 v196, v198
	v_permlane16_swap_b32_e32 v197, v199
	v_permlane16_swap_b32_e32 v200, v202
	v_permlane16_swap_b32_e32 v201, v203
	s_and_saveexec_b64 s[0:1], vcc
	global_store_dwordx4 v[204:205], v[196:199], off
	global_store_dwordx4 v[204:205], v[200:203], off offset:64
	s_or_b64 exec, exec, s[0:1]
	v_lshl_add_u64 v[204:205], v[204:205], 0, v[208:209]
	v_add_u32_e32 v206, 16, v206
	v_add_f32_e32 v94, v94, v210
	v_add_f32_e32 v95, v95, v211
	v_add_f32_e32 v96, v96, v212
	v_add_f32_e32 v97, v97, v213
	v_mul_f32_e32 v94, 0xbfb8aa3b, v94
	v_mul_f32_e32 v95, 0xbfb8aa3b, v95
	v_mul_f32_e32 v96, 0xbfb8aa3b, v96
	v_mul_f32_e32 v97, 0xbfb8aa3b, v97
	v_exp_f32_e32 v94, v94
	v_exp_f32_e32 v95, v95
	v_exp_f32_e32 v96, v96
	v_exp_f32_e32 v97, v97
	s_nop 0
	v_add_f32_e32 v94, 1.0, v94
	v_add_f32_e32 v95, 1.0, v95
	v_add_f32_e32 v96, 1.0, v96
	v_add_f32_e32 v97, 1.0, v97
	v_rcp_f32_e32 v226, v94
	v_rcp_f32_e32 v227, v95
	v_rcp_f32_e32 v228, v96
	v_rcp_f32_e32 v229, v97
	s_nop 0
	v_fma_f32 v94, -v94, v226, 1.0
	v_fma_f32 v95, -v95, v227, 1.0
	v_fma_f32 v96, -v96, v228, 1.0
	v_fma_f32 v97, -v97, v229, 1.0
	v_fma_f32 v94, v94, v226, v226
	v_fma_f32 v95, v95, v227, v227
	v_fma_f32 v96, v96, v228, v228
	v_fma_f32 v97, v97, v229, v229
	v_mul_f32_e32 v94, s12, v94
	v_mul_f32_e32 v95, s12, v95
	v_mul_f32_e32 v96, s12, v96
	v_mul_f32_e32 v97, s12, v97
	v_add_f32_e32 v90, v90, v214
	v_add_f32_e32 v91, v91, v215
	v_add_f32_e32 v92, v92, v216
	v_add_f32_e32 v93, v93, v217
	v_mul_f32_e32 v90, 0xbfb8aa3b, v90
	v_mul_f32_e32 v91, 0xbfb8aa3b, v91
	v_mul_f32_e32 v92, 0xbfb8aa3b, v92
	v_mul_f32_e32 v93, 0xbfb8aa3b, v93
	v_exp_f32_e32 v90, v90
	v_exp_f32_e32 v91, v91
	v_exp_f32_e32 v92, v92
	v_exp_f32_e32 v93, v93
	s_nop 0
	v_add_f32_e32 v90, 1.0, v90
	v_add_f32_e32 v91, 1.0, v91
	v_add_f32_e32 v92, 1.0, v92
	v_add_f32_e32 v93, 1.0, v93
	v_rcp_f32_e32 v226, v90
	v_rcp_f32_e32 v227, v91
	v_rcp_f32_e32 v228, v92
	v_rcp_f32_e32 v229, v93
	s_nop 0
	v_fma_f32 v90, -v90, v226, 1.0
	v_fma_f32 v91, -v91, v227, 1.0
	v_fma_f32 v92, -v92, v228, 1.0
	v_fma_f32 v93, -v93, v229, 1.0
	v_fma_f32 v90, v90, v226, v226
	v_fma_f32 v91, v91, v227, v227
	v_fma_f32 v92, v92, v228, v228
	v_fma_f32 v93, v93, v229, v229
	v_mul_f32_e32 v90, s12, v90
	v_mul_f32_e32 v91, s12, v91
	v_mul_f32_e32 v92, s12, v92
	v_mul_f32_e32 v93, s12, v93
	v_add_f32_e32 v86, v86, v218
	v_add_f32_e32 v87, v87, v219
	v_add_f32_e32 v88, v88, v220
	v_add_f32_e32 v89, v89, v221
	v_mul_f32_e32 v86, 0xbfb8aa3b, v86
	v_mul_f32_e32 v87, 0xbfb8aa3b, v87
	v_mul_f32_e32 v88, 0xbfb8aa3b, v88
	v_mul_f32_e32 v89, 0xbfb8aa3b, v89
	v_exp_f32_e32 v86, v86
	v_exp_f32_e32 v87, v87
	v_exp_f32_e32 v88, v88
	v_exp_f32_e32 v89, v89
	s_nop 0
	v_add_f32_e32 v86, 1.0, v86
	v_add_f32_e32 v87, 1.0, v87
	v_add_f32_e32 v88, 1.0, v88
	v_add_f32_e32 v89, 1.0, v89
	v_rcp_f32_e32 v226, v86
	v_rcp_f32_e32 v227, v87
	v_rcp_f32_e32 v228, v88
	v_rcp_f32_e32 v229, v89
	s_nop 0
	v_fma_f32 v86, -v86, v226, 1.0
	v_fma_f32 v87, -v87, v227, 1.0
	v_fma_f32 v88, -v88, v228, 1.0
	v_fma_f32 v89, -v89, v229, 1.0
	v_fma_f32 v86, v86, v226, v226
	v_fma_f32 v87, v87, v227, v227
	v_fma_f32 v88, v88, v228, v228
	v_fma_f32 v89, v89, v229, v229
	v_mul_f32_e32 v86, s12, v86
	v_mul_f32_e32 v87, s12, v87
	v_mul_f32_e32 v88, s12, v88
	v_mul_f32_e32 v89, s12, v89
	v_add_f32_e32 v82, v82, v222
	v_add_f32_e32 v83, v83, v223
	v_add_f32_e32 v84, v84, v224
	v_add_f32_e32 v85, v85, v225
	v_mul_f32_e32 v82, 0xbfb8aa3b, v82
	v_mul_f32_e32 v83, 0xbfb8aa3b, v83
	v_mul_f32_e32 v84, 0xbfb8aa3b, v84
	v_mul_f32_e32 v85, 0xbfb8aa3b, v85
	v_exp_f32_e32 v82, v82
	v_exp_f32_e32 v83, v83
	v_exp_f32_e32 v84, v84
	v_exp_f32_e32 v85, v85
	s_nop 0
	v_add_f32_e32 v82, 1.0, v82
	v_add_f32_e32 v83, 1.0, v83
	v_add_f32_e32 v84, 1.0, v84
	v_add_f32_e32 v85, 1.0, v85
	v_rcp_f32_e32 v226, v82
	v_rcp_f32_e32 v227, v83
	v_rcp_f32_e32 v228, v84
	v_rcp_f32_e32 v229, v85
	s_nop 0
	v_fma_f32 v82, -v82, v226, 1.0
	v_fma_f32 v83, -v83, v227, 1.0
	v_fma_f32 v84, -v84, v228, 1.0
	v_fma_f32 v85, -v85, v229, 1.0
	v_fma_f32 v82, v82, v226, v226
	v_fma_f32 v83, v83, v227, v227
	v_fma_f32 v84, v84, v228, v228
	v_fma_f32 v85, v85, v229, v229
	v_mul_f32_e32 v82, s12, v82
	v_mul_f32_e32 v83, s12, v83
	v_mul_f32_e32 v84, s12, v84
	v_mul_f32_e32 v85, s12, v85
	v_cvt_pk_f16_f32 v196, v94, v95
	v_cvt_pk_f16_f32 v197, v96, v97
	v_cvt_pk_f16_f32 v198, v90, v91
	v_cvt_pk_f16_f32 v199, v92, v93
	v_cvt_pk_f16_f32 v200, v86, v87
	v_cvt_pk_f16_f32 v201, v88, v89
	v_cvt_pk_f16_f32 v202, v82, v83
	v_cvt_pk_f16_f32 v203, v84, v85
	v_cmp_gt_i32_e32 vcc, s38, v206
	s_nop 0
	v_permlane16_swap_b32_e32 v196, v198
	v_permlane16_swap_b32_e32 v197, v199
	v_permlane16_swap_b32_e32 v200, v202
	v_permlane16_swap_b32_e32 v201, v203
	s_and_saveexec_b64 s[0:1], vcc
	global_store_dwordx4 v[204:205], v[196:199], off
	global_store_dwordx4 v[204:205], v[200:203], off offset:64
	s_or_b64 exec, exec, s[0:1]
	v_lshl_add_u64 v[204:205], v[204:205], 0, v[208:209]
	v_add_u32_e32 v206, 16, v206
	v_add_f32_e32 v78, v78, v210
	v_add_f32_e32 v79, v79, v211
	v_add_f32_e32 v80, v80, v212
	v_add_f32_e32 v81, v81, v213
	v_mul_f32_e32 v78, 0xbfb8aa3b, v78
	v_mul_f32_e32 v79, 0xbfb8aa3b, v79
	v_mul_f32_e32 v80, 0xbfb8aa3b, v80
	v_mul_f32_e32 v81, 0xbfb8aa3b, v81
	v_exp_f32_e32 v78, v78
	v_exp_f32_e32 v79, v79
	v_exp_f32_e32 v80, v80
	v_exp_f32_e32 v81, v81
	s_nop 0
	v_add_f32_e32 v78, 1.0, v78
	v_add_f32_e32 v79, 1.0, v79
	v_add_f32_e32 v80, 1.0, v80
	v_add_f32_e32 v81, 1.0, v81
	v_rcp_f32_e32 v226, v78
	v_rcp_f32_e32 v227, v79
	v_rcp_f32_e32 v228, v80
	v_rcp_f32_e32 v229, v81
	s_nop 0
	v_fma_f32 v78, -v78, v226, 1.0
	v_fma_f32 v79, -v79, v227, 1.0
	v_fma_f32 v80, -v80, v228, 1.0
	v_fma_f32 v81, -v81, v229, 1.0
	v_fma_f32 v78, v78, v226, v226
	v_fma_f32 v79, v79, v227, v227
	v_fma_f32 v80, v80, v228, v228
	v_fma_f32 v81, v81, v229, v229
	v_mul_f32_e32 v78, s12, v78
	v_mul_f32_e32 v79, s12, v79
	v_mul_f32_e32 v80, s12, v80
	v_mul_f32_e32 v81, s12, v81
	v_add_f32_e32 v74, v74, v214
	v_add_f32_e32 v75, v75, v215
	v_add_f32_e32 v76, v76, v216
	v_add_f32_e32 v77, v77, v217
	v_mul_f32_e32 v74, 0xbfb8aa3b, v74
	v_mul_f32_e32 v75, 0xbfb8aa3b, v75
	v_mul_f32_e32 v76, 0xbfb8aa3b, v76
	v_mul_f32_e32 v77, 0xbfb8aa3b, v77
	v_exp_f32_e32 v74, v74
	v_exp_f32_e32 v75, v75
	v_exp_f32_e32 v76, v76
	v_exp_f32_e32 v77, v77
	s_nop 0
	v_add_f32_e32 v74, 1.0, v74
	v_add_f32_e32 v75, 1.0, v75
	v_add_f32_e32 v76, 1.0, v76
	v_add_f32_e32 v77, 1.0, v77
	v_rcp_f32_e32 v226, v74
	v_rcp_f32_e32 v227, v75
	v_rcp_f32_e32 v228, v76
	v_rcp_f32_e32 v229, v77
	s_nop 0
	v_fma_f32 v74, -v74, v226, 1.0
	v_fma_f32 v75, -v75, v227, 1.0
	v_fma_f32 v76, -v76, v228, 1.0
	v_fma_f32 v77, -v77, v229, 1.0
	v_fma_f32 v74, v74, v226, v226
	v_fma_f32 v75, v75, v227, v227
	v_fma_f32 v76, v76, v228, v228
	v_fma_f32 v77, v77, v229, v229
	v_mul_f32_e32 v74, s12, v74
	v_mul_f32_e32 v75, s12, v75
	v_mul_f32_e32 v76, s12, v76
	v_mul_f32_e32 v77, s12, v77
	v_add_f32_e32 v70, v70, v218
	v_add_f32_e32 v71, v71, v219
	v_add_f32_e32 v72, v72, v220
	v_add_f32_e32 v73, v73, v221
	v_mul_f32_e32 v70, 0xbfb8aa3b, v70
	v_mul_f32_e32 v71, 0xbfb8aa3b, v71
	v_mul_f32_e32 v72, 0xbfb8aa3b, v72
	v_mul_f32_e32 v73, 0xbfb8aa3b, v73
	v_exp_f32_e32 v70, v70
	v_exp_f32_e32 v71, v71
	v_exp_f32_e32 v72, v72
	v_exp_f32_e32 v73, v73
	s_nop 0
	v_add_f32_e32 v70, 1.0, v70
	v_add_f32_e32 v71, 1.0, v71
	v_add_f32_e32 v72, 1.0, v72
	v_add_f32_e32 v73, 1.0, v73
	v_rcp_f32_e32 v226, v70
	v_rcp_f32_e32 v227, v71
	v_rcp_f32_e32 v228, v72
	v_rcp_f32_e32 v229, v73
	s_nop 0
	v_fma_f32 v70, -v70, v226, 1.0
	v_fma_f32 v71, -v71, v227, 1.0
	v_fma_f32 v72, -v72, v228, 1.0
	v_fma_f32 v73, -v73, v229, 1.0
	v_fma_f32 v70, v70, v226, v226
	v_fma_f32 v71, v71, v227, v227
	v_fma_f32 v72, v72, v228, v228
	v_fma_f32 v73, v73, v229, v229
	v_mul_f32_e32 v70, s12, v70
	v_mul_f32_e32 v71, s12, v71
	v_mul_f32_e32 v72, s12, v72
	v_mul_f32_e32 v73, s12, v73
	v_add_f32_e32 v66, v66, v222
	v_add_f32_e32 v67, v67, v223
	v_add_f32_e32 v68, v68, v224
	v_add_f32_e32 v69, v69, v225
	v_mul_f32_e32 v66, 0xbfb8aa3b, v66
	v_mul_f32_e32 v67, 0xbfb8aa3b, v67
	v_mul_f32_e32 v68, 0xbfb8aa3b, v68
	v_mul_f32_e32 v69, 0xbfb8aa3b, v69
	v_exp_f32_e32 v66, v66
	v_exp_f32_e32 v67, v67
	v_exp_f32_e32 v68, v68
	v_exp_f32_e32 v69, v69
	s_nop 0
	v_add_f32_e32 v66, 1.0, v66
	v_add_f32_e32 v67, 1.0, v67
	v_add_f32_e32 v68, 1.0, v68
	v_add_f32_e32 v69, 1.0, v69
	v_rcp_f32_e32 v226, v66
	v_rcp_f32_e32 v227, v67
	v_rcp_f32_e32 v228, v68
	v_rcp_f32_e32 v229, v69
	s_nop 0
	v_fma_f32 v66, -v66, v226, 1.0
	v_fma_f32 v67, -v67, v227, 1.0
	v_fma_f32 v68, -v68, v228, 1.0
	v_fma_f32 v69, -v69, v229, 1.0
	v_fma_f32 v66, v66, v226, v226
	v_fma_f32 v67, v67, v227, v227
	v_fma_f32 v68, v68, v228, v228
	v_fma_f32 v69, v69, v229, v229
	v_mul_f32_e32 v66, s12, v66
	v_mul_f32_e32 v67, s12, v67
	v_mul_f32_e32 v68, s12, v68
	v_mul_f32_e32 v69, s12, v69
	v_cvt_pk_f16_f32 v196, v78, v79
	v_cvt_pk_f16_f32 v197, v80, v81
	v_cvt_pk_f16_f32 v198, v74, v75
	v_cvt_pk_f16_f32 v199, v76, v77
	v_cvt_pk_f16_f32 v200, v70, v71
	v_cvt_pk_f16_f32 v201, v72, v73
	v_cvt_pk_f16_f32 v202, v66, v67
	v_cvt_pk_f16_f32 v203, v68, v69
	v_cmp_gt_i32_e32 vcc, s38, v206
	s_nop 0
	v_permlane16_swap_b32_e32 v196, v198
	v_permlane16_swap_b32_e32 v197, v199
	v_permlane16_swap_b32_e32 v200, v202
	v_permlane16_swap_b32_e32 v201, v203
	s_and_saveexec_b64 s[0:1], vcc
	global_store_dwordx4 v[204:205], v[196:199], off
	global_store_dwordx4 v[204:205], v[200:203], off offset:64
	s_or_b64 exec, exec, s[0:1]
	v_lshl_add_u64 v[204:205], v[204:205], 0, v[208:209]
	v_add_u32_e32 v206, 16, v206
	v_add_f32_e32 v62, v62, v210
	v_add_f32_e32 v63, v63, v211
	v_add_f32_e32 v64, v64, v212
	v_add_f32_e32 v65, v65, v213
	v_mul_f32_e32 v62, 0xbfb8aa3b, v62
	v_mul_f32_e32 v63, 0xbfb8aa3b, v63
	v_mul_f32_e32 v64, 0xbfb8aa3b, v64
	v_mul_f32_e32 v65, 0xbfb8aa3b, v65
	v_exp_f32_e32 v62, v62
	v_exp_f32_e32 v63, v63
	v_exp_f32_e32 v64, v64
	v_exp_f32_e32 v65, v65
	s_nop 0
	v_add_f32_e32 v62, 1.0, v62
	v_add_f32_e32 v63, 1.0, v63
	v_add_f32_e32 v64, 1.0, v64
	v_add_f32_e32 v65, 1.0, v65
	v_rcp_f32_e32 v226, v62
	v_rcp_f32_e32 v227, v63
	v_rcp_f32_e32 v228, v64
	v_rcp_f32_e32 v229, v65
	s_nop 0
	v_fma_f32 v62, -v62, v226, 1.0
	v_fma_f32 v63, -v63, v227, 1.0
	v_fma_f32 v64, -v64, v228, 1.0
	v_fma_f32 v65, -v65, v229, 1.0
	v_fma_f32 v62, v62, v226, v226
	v_fma_f32 v63, v63, v227, v227
	v_fma_f32 v64, v64, v228, v228
	v_fma_f32 v65, v65, v229, v229
	v_mul_f32_e32 v62, s12, v62
	v_mul_f32_e32 v63, s12, v63
	v_mul_f32_e32 v64, s12, v64
	v_mul_f32_e32 v65, s12, v65
	v_add_f32_e32 v58, v58, v214
	v_add_f32_e32 v59, v59, v215
	v_add_f32_e32 v60, v60, v216
	v_add_f32_e32 v61, v61, v217
	v_mul_f32_e32 v58, 0xbfb8aa3b, v58
	v_mul_f32_e32 v59, 0xbfb8aa3b, v59
	v_mul_f32_e32 v60, 0xbfb8aa3b, v60
	v_mul_f32_e32 v61, 0xbfb8aa3b, v61
	v_exp_f32_e32 v58, v58
	v_exp_f32_e32 v59, v59
	v_exp_f32_e32 v60, v60
	v_exp_f32_e32 v61, v61
	s_nop 0
	v_add_f32_e32 v58, 1.0, v58
	v_add_f32_e32 v59, 1.0, v59
	v_add_f32_e32 v60, 1.0, v60
	v_add_f32_e32 v61, 1.0, v61
	v_rcp_f32_e32 v226, v58
	v_rcp_f32_e32 v227, v59
	v_rcp_f32_e32 v228, v60
	v_rcp_f32_e32 v229, v61
	s_nop 0
	v_fma_f32 v58, -v58, v226, 1.0
	v_fma_f32 v59, -v59, v227, 1.0
	v_fma_f32 v60, -v60, v228, 1.0
	v_fma_f32 v61, -v61, v229, 1.0
	v_fma_f32 v58, v58, v226, v226
	v_fma_f32 v59, v59, v227, v227
	v_fma_f32 v60, v60, v228, v228
	v_fma_f32 v61, v61, v229, v229
	v_mul_f32_e32 v58, s12, v58
	v_mul_f32_e32 v59, s12, v59
	v_mul_f32_e32 v60, s12, v60
	v_mul_f32_e32 v61, s12, v61
	v_add_f32_e32 v54, v54, v218
	v_add_f32_e32 v55, v55, v219
	v_add_f32_e32 v56, v56, v220
	v_add_f32_e32 v57, v57, v221
	v_mul_f32_e32 v54, 0xbfb8aa3b, v54
	v_mul_f32_e32 v55, 0xbfb8aa3b, v55
	v_mul_f32_e32 v56, 0xbfb8aa3b, v56
	v_mul_f32_e32 v57, 0xbfb8aa3b, v57
	v_exp_f32_e32 v54, v54
	v_exp_f32_e32 v55, v55
	v_exp_f32_e32 v56, v56
	v_exp_f32_e32 v57, v57
	s_nop 0
	v_add_f32_e32 v54, 1.0, v54
	v_add_f32_e32 v55, 1.0, v55
	v_add_f32_e32 v56, 1.0, v56
	v_add_f32_e32 v57, 1.0, v57
	v_rcp_f32_e32 v226, v54
	v_rcp_f32_e32 v227, v55
	v_rcp_f32_e32 v228, v56
	v_rcp_f32_e32 v229, v57
	s_nop 0
	v_fma_f32 v54, -v54, v226, 1.0
	v_fma_f32 v55, -v55, v227, 1.0
	v_fma_f32 v56, -v56, v228, 1.0
	v_fma_f32 v57, -v57, v229, 1.0
	v_fma_f32 v54, v54, v226, v226
	v_fma_f32 v55, v55, v227, v227
	v_fma_f32 v56, v56, v228, v228
	v_fma_f32 v57, v57, v229, v229
	v_mul_f32_e32 v54, s12, v54
	v_mul_f32_e32 v55, s12, v55
	v_mul_f32_e32 v56, s12, v56
	v_mul_f32_e32 v57, s12, v57
	v_add_f32_e32 v50, v50, v222
	v_add_f32_e32 v51, v51, v223
	v_add_f32_e32 v52, v52, v224
	v_add_f32_e32 v53, v53, v225
	v_mul_f32_e32 v50, 0xbfb8aa3b, v50
	v_mul_f32_e32 v51, 0xbfb8aa3b, v51
	v_mul_f32_e32 v52, 0xbfb8aa3b, v52
	v_mul_f32_e32 v53, 0xbfb8aa3b, v53
	v_exp_f32_e32 v50, v50
	v_exp_f32_e32 v51, v51
	v_exp_f32_e32 v52, v52
	v_exp_f32_e32 v53, v53
	s_nop 0
	v_add_f32_e32 v50, 1.0, v50
	v_add_f32_e32 v51, 1.0, v51
	v_add_f32_e32 v52, 1.0, v52
	v_add_f32_e32 v53, 1.0, v53
	v_rcp_f32_e32 v226, v50
	v_rcp_f32_e32 v227, v51
	v_rcp_f32_e32 v228, v52
	v_rcp_f32_e32 v229, v53
	s_nop 0
	v_fma_f32 v50, -v50, v226, 1.0
	v_fma_f32 v51, -v51, v227, 1.0
	v_fma_f32 v52, -v52, v228, 1.0
	v_fma_f32 v53, -v53, v229, 1.0
	v_fma_f32 v50, v50, v226, v226
	v_fma_f32 v51, v51, v227, v227
	v_fma_f32 v52, v52, v228, v228
	v_fma_f32 v53, v53, v229, v229
	v_mul_f32_e32 v50, s12, v50
	v_mul_f32_e32 v51, s12, v51
	v_mul_f32_e32 v52, s12, v52
	v_mul_f32_e32 v53, s12, v53
	v_cvt_pk_f16_f32 v196, v62, v63
	v_cvt_pk_f16_f32 v197, v64, v65
	v_cvt_pk_f16_f32 v198, v58, v59
	v_cvt_pk_f16_f32 v199, v60, v61
	v_cvt_pk_f16_f32 v200, v54, v55
	v_cvt_pk_f16_f32 v201, v56, v57
	v_cvt_pk_f16_f32 v202, v50, v51
	v_cvt_pk_f16_f32 v203, v52, v53
	v_cmp_gt_i32_e32 vcc, s38, v206
	s_nop 0
	v_permlane16_swap_b32_e32 v196, v198
	v_permlane16_swap_b32_e32 v197, v199
	v_permlane16_swap_b32_e32 v200, v202
	v_permlane16_swap_b32_e32 v201, v203
	s_and_saveexec_b64 s[0:1], vcc
	global_store_dwordx4 v[204:205], v[196:199], off
	global_store_dwordx4 v[204:205], v[200:203], off offset:64
	s_or_b64 exec, exec, s[0:1]
	v_lshl_add_u64 v[204:205], v[204:205], 0, v[208:209]
	v_add_u32_e32 v206, 16, v206
	v_add_f32_e32 v46, v46, v210
	v_add_f32_e32 v47, v47, v211
	v_add_f32_e32 v48, v48, v212
	v_add_f32_e32 v49, v49, v213
	v_mul_f32_e32 v46, 0xbfb8aa3b, v46
	v_mul_f32_e32 v47, 0xbfb8aa3b, v47
	v_mul_f32_e32 v48, 0xbfb8aa3b, v48
	v_mul_f32_e32 v49, 0xbfb8aa3b, v49
	v_exp_f32_e32 v46, v46
	v_exp_f32_e32 v47, v47
	v_exp_f32_e32 v48, v48
	v_exp_f32_e32 v49, v49
	s_nop 0
	v_add_f32_e32 v46, 1.0, v46
	v_add_f32_e32 v47, 1.0, v47
	v_add_f32_e32 v48, 1.0, v48
	v_add_f32_e32 v49, 1.0, v49
	v_rcp_f32_e32 v226, v46
	v_rcp_f32_e32 v227, v47
	v_rcp_f32_e32 v228, v48
	v_rcp_f32_e32 v229, v49
	s_nop 0
	v_fma_f32 v46, -v46, v226, 1.0
	v_fma_f32 v47, -v47, v227, 1.0
	v_fma_f32 v48, -v48, v228, 1.0
	v_fma_f32 v49, -v49, v229, 1.0
	v_fma_f32 v46, v46, v226, v226
	v_fma_f32 v47, v47, v227, v227
	v_fma_f32 v48, v48, v228, v228
	v_fma_f32 v49, v49, v229, v229
	v_mul_f32_e32 v46, s12, v46
	v_mul_f32_e32 v47, s12, v47
	v_mul_f32_e32 v48, s12, v48
	v_mul_f32_e32 v49, s12, v49
	v_add_f32_e32 v42, v42, v214
	v_add_f32_e32 v43, v43, v215
	v_add_f32_e32 v44, v44, v216
	v_add_f32_e32 v45, v45, v217
	v_mul_f32_e32 v42, 0xbfb8aa3b, v42
	v_mul_f32_e32 v43, 0xbfb8aa3b, v43
	v_mul_f32_e32 v44, 0xbfb8aa3b, v44
	v_mul_f32_e32 v45, 0xbfb8aa3b, v45
	v_exp_f32_e32 v42, v42
	v_exp_f32_e32 v43, v43
	v_exp_f32_e32 v44, v44
	v_exp_f32_e32 v45, v45
	s_nop 0
	v_add_f32_e32 v42, 1.0, v42
	v_add_f32_e32 v43, 1.0, v43
	v_add_f32_e32 v44, 1.0, v44
	v_add_f32_e32 v45, 1.0, v45
	v_rcp_f32_e32 v226, v42
	v_rcp_f32_e32 v227, v43
	v_rcp_f32_e32 v228, v44
	v_rcp_f32_e32 v229, v45
	s_nop 0
	v_fma_f32 v42, -v42, v226, 1.0
	v_fma_f32 v43, -v43, v227, 1.0
	v_fma_f32 v44, -v44, v228, 1.0
	v_fma_f32 v45, -v45, v229, 1.0
	v_fma_f32 v42, v42, v226, v226
	v_fma_f32 v43, v43, v227, v227
	v_fma_f32 v44, v44, v228, v228
	v_fma_f32 v45, v45, v229, v229
	v_mul_f32_e32 v42, s12, v42
	v_mul_f32_e32 v43, s12, v43
	v_mul_f32_e32 v44, s12, v44
	v_mul_f32_e32 v45, s12, v45
	v_add_f32_e32 v38, v38, v218
	v_add_f32_e32 v39, v39, v219
	v_add_f32_e32 v40, v40, v220
	v_add_f32_e32 v41, v41, v221
	v_mul_f32_e32 v38, 0xbfb8aa3b, v38
	v_mul_f32_e32 v39, 0xbfb8aa3b, v39
	v_mul_f32_e32 v40, 0xbfb8aa3b, v40
	v_mul_f32_e32 v41, 0xbfb8aa3b, v41
	v_exp_f32_e32 v38, v38
	v_exp_f32_e32 v39, v39
	v_exp_f32_e32 v40, v40
	v_exp_f32_e32 v41, v41
	s_nop 0
	v_add_f32_e32 v38, 1.0, v38
	v_add_f32_e32 v39, 1.0, v39
	v_add_f32_e32 v40, 1.0, v40
	v_add_f32_e32 v41, 1.0, v41
	v_rcp_f32_e32 v226, v38
	v_rcp_f32_e32 v227, v39
	v_rcp_f32_e32 v228, v40
	v_rcp_f32_e32 v229, v41
	s_nop 0
	v_fma_f32 v38, -v38, v226, 1.0
	v_fma_f32 v39, -v39, v227, 1.0
	v_fma_f32 v40, -v40, v228, 1.0
	v_fma_f32 v41, -v41, v229, 1.0
	v_fma_f32 v38, v38, v226, v226
	v_fma_f32 v39, v39, v227, v227
	v_fma_f32 v40, v40, v228, v228
	v_fma_f32 v41, v41, v229, v229
	v_mul_f32_e32 v38, s12, v38
	v_mul_f32_e32 v39, s12, v39
	v_mul_f32_e32 v40, s12, v40
	v_mul_f32_e32 v41, s12, v41
	v_add_f32_e32 v34, v34, v222
	v_add_f32_e32 v35, v35, v223
	v_add_f32_e32 v36, v36, v224
	v_add_f32_e32 v37, v37, v225
	v_mul_f32_e32 v34, 0xbfb8aa3b, v34
	v_mul_f32_e32 v35, 0xbfb8aa3b, v35
	v_mul_f32_e32 v36, 0xbfb8aa3b, v36
	v_mul_f32_e32 v37, 0xbfb8aa3b, v37
	v_exp_f32_e32 v34, v34
	v_exp_f32_e32 v35, v35
	v_exp_f32_e32 v36, v36
	v_exp_f32_e32 v37, v37
	s_nop 0
	v_add_f32_e32 v34, 1.0, v34
	v_add_f32_e32 v35, 1.0, v35
	v_add_f32_e32 v36, 1.0, v36
	v_add_f32_e32 v37, 1.0, v37
	v_rcp_f32_e32 v226, v34
	v_rcp_f32_e32 v227, v35
	v_rcp_f32_e32 v228, v36
	v_rcp_f32_e32 v229, v37
	s_nop 0
	v_fma_f32 v34, -v34, v226, 1.0
	v_fma_f32 v35, -v35, v227, 1.0
	v_fma_f32 v36, -v36, v228, 1.0
	v_fma_f32 v37, -v37, v229, 1.0
	v_fma_f32 v34, v34, v226, v226
	v_fma_f32 v35, v35, v227, v227
	v_fma_f32 v36, v36, v228, v228
	v_fma_f32 v37, v37, v229, v229
	v_mul_f32_e32 v34, s12, v34
	v_mul_f32_e32 v35, s12, v35
	v_mul_f32_e32 v36, s12, v36
	v_mul_f32_e32 v37, s12, v37
	v_cvt_pk_f16_f32 v196, v46, v47
	v_cvt_pk_f16_f32 v197, v48, v49
	v_cvt_pk_f16_f32 v198, v42, v43
	v_cvt_pk_f16_f32 v199, v44, v45
	v_cvt_pk_f16_f32 v200, v38, v39
	v_cvt_pk_f16_f32 v201, v40, v41
	v_cvt_pk_f16_f32 v202, v34, v35
	v_cvt_pk_f16_f32 v203, v36, v37
	v_cmp_gt_i32_e32 vcc, s38, v206
	s_nop 0
	v_permlane16_swap_b32_e32 v196, v198
	v_permlane16_swap_b32_e32 v197, v199
	v_permlane16_swap_b32_e32 v200, v202
	v_permlane16_swap_b32_e32 v201, v203
	s_and_saveexec_b64 s[0:1], vcc
	global_store_dwordx4 v[204:205], v[196:199], off
	global_store_dwordx4 v[204:205], v[200:203], off offset:64
	s_or_b64 exec, exec, s[0:1]
	v_lshl_add_u64 v[204:205], v[204:205], 0, v[208:209]
	v_add_u32_e32 v206, 16, v206
	v_add_f32_e32 v30, v30, v210
	v_add_f32_e32 v31, v31, v211
	v_add_f32_e32 v32, v32, v212
	v_add_f32_e32 v33, v33, v213
	v_mul_f32_e32 v30, 0xbfb8aa3b, v30
	v_mul_f32_e32 v31, 0xbfb8aa3b, v31
	v_mul_f32_e32 v32, 0xbfb8aa3b, v32
	v_mul_f32_e32 v33, 0xbfb8aa3b, v33
	v_exp_f32_e32 v30, v30
	v_exp_f32_e32 v31, v31
	v_exp_f32_e32 v32, v32
	v_exp_f32_e32 v33, v33
	s_nop 0
	v_add_f32_e32 v30, 1.0, v30
	v_add_f32_e32 v31, 1.0, v31
	v_add_f32_e32 v32, 1.0, v32
	v_add_f32_e32 v33, 1.0, v33
	v_rcp_f32_e32 v226, v30
	v_rcp_f32_e32 v227, v31
	v_rcp_f32_e32 v228, v32
	v_rcp_f32_e32 v229, v33
	s_nop 0
	v_fma_f32 v30, -v30, v226, 1.0
	v_fma_f32 v31, -v31, v227, 1.0
	v_fma_f32 v32, -v32, v228, 1.0
	v_fma_f32 v33, -v33, v229, 1.0
	v_fma_f32 v30, v30, v226, v226
	v_fma_f32 v31, v31, v227, v227
	v_fma_f32 v32, v32, v228, v228
	v_fma_f32 v33, v33, v229, v229
	v_mul_f32_e32 v30, s12, v30
	v_mul_f32_e32 v31, s12, v31
	v_mul_f32_e32 v32, s12, v32
	v_mul_f32_e32 v33, s12, v33
	v_add_f32_e32 v26, v26, v214
	v_add_f32_e32 v27, v27, v215
	v_add_f32_e32 v28, v28, v216
	v_add_f32_e32 v29, v29, v217
	v_mul_f32_e32 v26, 0xbfb8aa3b, v26
	v_mul_f32_e32 v27, 0xbfb8aa3b, v27
	v_mul_f32_e32 v28, 0xbfb8aa3b, v28
	v_mul_f32_e32 v29, 0xbfb8aa3b, v29
	v_exp_f32_e32 v26, v26
	v_exp_f32_e32 v27, v27
	v_exp_f32_e32 v28, v28
	v_exp_f32_e32 v29, v29
	s_nop 0
	v_add_f32_e32 v26, 1.0, v26
	v_add_f32_e32 v27, 1.0, v27
	v_add_f32_e32 v28, 1.0, v28
	v_add_f32_e32 v29, 1.0, v29
	v_rcp_f32_e32 v226, v26
	v_rcp_f32_e32 v227, v27
	v_rcp_f32_e32 v228, v28
	v_rcp_f32_e32 v229, v29
	s_nop 0
	v_fma_f32 v26, -v26, v226, 1.0
	v_fma_f32 v27, -v27, v227, 1.0
	v_fma_f32 v28, -v28, v228, 1.0
	v_fma_f32 v29, -v29, v229, 1.0
	v_fma_f32 v26, v26, v226, v226
	v_fma_f32 v27, v27, v227, v227
	v_fma_f32 v28, v28, v228, v228
	v_fma_f32 v29, v29, v229, v229
	v_mul_f32_e32 v26, s12, v26
	v_mul_f32_e32 v27, s12, v27
	v_mul_f32_e32 v28, s12, v28
	v_mul_f32_e32 v29, s12, v29
	v_add_f32_e32 v22, v22, v218
	v_add_f32_e32 v23, v23, v219
	v_add_f32_e32 v24, v24, v220
	v_add_f32_e32 v25, v25, v221
	v_mul_f32_e32 v22, 0xbfb8aa3b, v22
	v_mul_f32_e32 v23, 0xbfb8aa3b, v23
	v_mul_f32_e32 v24, 0xbfb8aa3b, v24
	v_mul_f32_e32 v25, 0xbfb8aa3b, v25
	v_exp_f32_e32 v22, v22
	v_exp_f32_e32 v23, v23
	v_exp_f32_e32 v24, v24
	v_exp_f32_e32 v25, v25
	s_nop 0
	v_add_f32_e32 v22, 1.0, v22
	v_add_f32_e32 v23, 1.0, v23
	v_add_f32_e32 v24, 1.0, v24
	v_add_f32_e32 v25, 1.0, v25
	v_rcp_f32_e32 v226, v22
	v_rcp_f32_e32 v227, v23
	v_rcp_f32_e32 v228, v24
	v_rcp_f32_e32 v229, v25
	s_nop 0
	v_fma_f32 v22, -v22, v226, 1.0
	v_fma_f32 v23, -v23, v227, 1.0
	v_fma_f32 v24, -v24, v228, 1.0
	v_fma_f32 v25, -v25, v229, 1.0
	v_fma_f32 v22, v22, v226, v226
	v_fma_f32 v23, v23, v227, v227
	v_fma_f32 v24, v24, v228, v228
	v_fma_f32 v25, v25, v229, v229
	v_mul_f32_e32 v22, s12, v22
	v_mul_f32_e32 v23, s12, v23
	v_mul_f32_e32 v24, s12, v24
	v_mul_f32_e32 v25, s12, v25
	v_add_f32_e32 v18, v18, v222
	v_add_f32_e32 v19, v19, v223
	v_add_f32_e32 v20, v20, v224
	v_add_f32_e32 v21, v21, v225
	v_mul_f32_e32 v18, 0xbfb8aa3b, v18
	v_mul_f32_e32 v19, 0xbfb8aa3b, v19
	v_mul_f32_e32 v20, 0xbfb8aa3b, v20
	v_mul_f32_e32 v21, 0xbfb8aa3b, v21
	v_exp_f32_e32 v18, v18
	v_exp_f32_e32 v19, v19
	v_exp_f32_e32 v20, v20
	v_exp_f32_e32 v21, v21
	s_nop 0
	v_add_f32_e32 v18, 1.0, v18
	v_add_f32_e32 v19, 1.0, v19
	v_add_f32_e32 v20, 1.0, v20
	v_add_f32_e32 v21, 1.0, v21
	v_rcp_f32_e32 v226, v18
	v_rcp_f32_e32 v227, v19
	v_rcp_f32_e32 v228, v20
	v_rcp_f32_e32 v229, v21
	s_nop 0
	v_fma_f32 v18, -v18, v226, 1.0
	v_fma_f32 v19, -v19, v227, 1.0
	v_fma_f32 v20, -v20, v228, 1.0
	v_fma_f32 v21, -v21, v229, 1.0
	v_fma_f32 v18, v18, v226, v226
	v_fma_f32 v19, v19, v227, v227
	v_fma_f32 v20, v20, v228, v228
	v_fma_f32 v21, v21, v229, v229
	v_mul_f32_e32 v18, s12, v18
	v_mul_f32_e32 v19, s12, v19
	v_mul_f32_e32 v20, s12, v20
	v_mul_f32_e32 v21, s12, v21
	v_cvt_pk_f16_f32 v196, v30, v31
	v_cvt_pk_f16_f32 v197, v32, v33
	v_cvt_pk_f16_f32 v198, v26, v27
	v_cvt_pk_f16_f32 v199, v28, v29
	v_cvt_pk_f16_f32 v200, v22, v23
	v_cvt_pk_f16_f32 v201, v24, v25
	v_cvt_pk_f16_f32 v202, v18, v19
	v_cvt_pk_f16_f32 v203, v20, v21
	v_cmp_gt_i32_e32 vcc, s38, v206
	s_nop 0
	v_permlane16_swap_b32_e32 v196, v198
	v_permlane16_swap_b32_e32 v197, v199
	v_permlane16_swap_b32_e32 v200, v202
	v_permlane16_swap_b32_e32 v201, v203
	s_and_saveexec_b64 s[0:1], vcc
	global_store_dwordx4 v[204:205], v[196:199], off
	global_store_dwordx4 v[204:205], v[200:203], off offset:64
	s_or_b64 exec, exec, s[0:1]
	v_lshl_add_u64 v[204:205], v[204:205], 0, v[208:209]
	v_add_u32_e32 v206, 16, v206
	v_add_f32_e32 v14, v14, v210
	v_add_f32_e32 v15, v15, v211
	v_add_f32_e32 v16, v16, v212
	v_add_f32_e32 v17, v17, v213
	v_mul_f32_e32 v14, 0xbfb8aa3b, v14
	v_mul_f32_e32 v15, 0xbfb8aa3b, v15
	v_mul_f32_e32 v16, 0xbfb8aa3b, v16
	v_mul_f32_e32 v17, 0xbfb8aa3b, v17
	v_exp_f32_e32 v14, v14
	v_exp_f32_e32 v15, v15
	v_exp_f32_e32 v16, v16
	v_exp_f32_e32 v17, v17
	s_nop 0
	v_add_f32_e32 v14, 1.0, v14
	v_add_f32_e32 v15, 1.0, v15
	v_add_f32_e32 v16, 1.0, v16
	v_add_f32_e32 v17, 1.0, v17
	v_rcp_f32_e32 v226, v14
	v_rcp_f32_e32 v227, v15
	v_rcp_f32_e32 v228, v16
	v_rcp_f32_e32 v229, v17
	s_nop 0
	v_fma_f32 v14, -v14, v226, 1.0
	v_fma_f32 v15, -v15, v227, 1.0
	v_fma_f32 v16, -v16, v228, 1.0
	v_fma_f32 v17, -v17, v229, 1.0
	v_fma_f32 v14, v14, v226, v226
	v_fma_f32 v15, v15, v227, v227
	v_fma_f32 v16, v16, v228, v228
	v_fma_f32 v17, v17, v229, v229
	v_mul_f32_e32 v14, s12, v14
	v_mul_f32_e32 v15, s12, v15
	v_mul_f32_e32 v16, s12, v16
	v_mul_f32_e32 v17, s12, v17
	v_add_f32_e32 v10, v10, v214
	v_add_f32_e32 v11, v11, v215
	v_add_f32_e32 v12, v12, v216
	v_add_f32_e32 v13, v13, v217
	v_mul_f32_e32 v10, 0xbfb8aa3b, v10
	v_mul_f32_e32 v11, 0xbfb8aa3b, v11
	v_mul_f32_e32 v12, 0xbfb8aa3b, v12
	v_mul_f32_e32 v13, 0xbfb8aa3b, v13
	v_exp_f32_e32 v10, v10
	v_exp_f32_e32 v11, v11
	v_exp_f32_e32 v12, v12
	v_exp_f32_e32 v13, v13
	s_nop 0
	v_add_f32_e32 v10, 1.0, v10
	v_add_f32_e32 v11, 1.0, v11
	v_add_f32_e32 v12, 1.0, v12
	v_add_f32_e32 v13, 1.0, v13
	v_rcp_f32_e32 v226, v10
	v_rcp_f32_e32 v227, v11
	v_rcp_f32_e32 v228, v12
	v_rcp_f32_e32 v229, v13
	s_nop 0
	v_fma_f32 v10, -v10, v226, 1.0
	v_fma_f32 v11, -v11, v227, 1.0
	v_fma_f32 v12, -v12, v228, 1.0
	v_fma_f32 v13, -v13, v229, 1.0
	v_fma_f32 v10, v10, v226, v226
	v_fma_f32 v11, v11, v227, v227
	v_fma_f32 v12, v12, v228, v228
	v_fma_f32 v13, v13, v229, v229
	v_mul_f32_e32 v10, s12, v10
	v_mul_f32_e32 v11, s12, v11
	v_mul_f32_e32 v12, s12, v12
	v_mul_f32_e32 v13, s12, v13
	v_add_f32_e32 v6, v6, v218
	v_add_f32_e32 v7, v7, v219
	v_add_f32_e32 v8, v8, v220
	v_add_f32_e32 v9, v9, v221
	v_mul_f32_e32 v6, 0xbfb8aa3b, v6
	v_mul_f32_e32 v7, 0xbfb8aa3b, v7
	v_mul_f32_e32 v8, 0xbfb8aa3b, v8
	v_mul_f32_e32 v9, 0xbfb8aa3b, v9
	v_exp_f32_e32 v6, v6
	v_exp_f32_e32 v7, v7
	v_exp_f32_e32 v8, v8
	v_exp_f32_e32 v9, v9
	s_nop 0
	v_add_f32_e32 v6, 1.0, v6
	v_add_f32_e32 v7, 1.0, v7
	v_add_f32_e32 v8, 1.0, v8
	v_add_f32_e32 v9, 1.0, v9
	v_rcp_f32_e32 v226, v6
	v_rcp_f32_e32 v227, v7
	v_rcp_f32_e32 v228, v8
	v_rcp_f32_e32 v229, v9
	s_nop 0
	v_fma_f32 v6, -v6, v226, 1.0
	v_fma_f32 v7, -v7, v227, 1.0
	v_fma_f32 v8, -v8, v228, 1.0
	v_fma_f32 v9, -v9, v229, 1.0
	v_fma_f32 v6, v6, v226, v226
	v_fma_f32 v7, v7, v227, v227
	v_fma_f32 v8, v8, v228, v228
	v_fma_f32 v9, v9, v229, v229
	v_mul_f32_e32 v6, s12, v6
	v_mul_f32_e32 v7, s12, v7
	v_mul_f32_e32 v8, s12, v8
	v_mul_f32_e32 v9, s12, v9
	v_add_f32_e32 v2, v2, v222
	v_add_f32_e32 v3, v3, v223
	v_add_f32_e32 v4, v4, v224
	v_add_f32_e32 v5, v5, v225
	v_mul_f32_e32 v2, 0xbfb8aa3b, v2
	v_mul_f32_e32 v3, 0xbfb8aa3b, v3
	v_mul_f32_e32 v4, 0xbfb8aa3b, v4
	v_mul_f32_e32 v5, 0xbfb8aa3b, v5
	v_exp_f32_e32 v2, v2
	v_exp_f32_e32 v3, v3
	v_exp_f32_e32 v4, v4
	v_exp_f32_e32 v5, v5
	s_nop 0
	v_add_f32_e32 v2, 1.0, v2
	v_add_f32_e32 v3, 1.0, v3
	v_add_f32_e32 v4, 1.0, v4
	v_add_f32_e32 v5, 1.0, v5
	v_rcp_f32_e32 v226, v2
	v_rcp_f32_e32 v227, v3
	v_rcp_f32_e32 v228, v4
	v_rcp_f32_e32 v229, v5
	s_nop 0
	v_fma_f32 v2, -v2, v226, 1.0
	v_fma_f32 v3, -v3, v227, 1.0
	v_fma_f32 v4, -v4, v228, 1.0
	v_fma_f32 v5, -v5, v229, 1.0
	v_fma_f32 v2, v2, v226, v226
	v_fma_f32 v3, v3, v227, v227
	v_fma_f32 v4, v4, v228, v228
	v_fma_f32 v5, v5, v229, v229
	v_mul_f32_e32 v2, s12, v2
	v_mul_f32_e32 v3, s12, v3
	v_mul_f32_e32 v4, s12, v4
	v_mul_f32_e32 v5, s12, v5
	v_cvt_pk_f16_f32 v196, v14, v15
	v_cvt_pk_f16_f32 v197, v16, v17
	v_cvt_pk_f16_f32 v198, v10, v11
	v_cvt_pk_f16_f32 v199, v12, v13
	v_cvt_pk_f16_f32 v200, v6, v7
	v_cvt_pk_f16_f32 v201, v8, v9
	v_cvt_pk_f16_f32 v202, v2, v3
	v_cvt_pk_f16_f32 v203, v4, v5
	v_cmp_gt_i32_e32 vcc, s38, v206
	s_nop 0
	v_permlane16_swap_b32_e32 v196, v198
	v_permlane16_swap_b32_e32 v197, v199
	v_permlane16_swap_b32_e32 v200, v202
	v_permlane16_swap_b32_e32 v201, v203
	s_and_saveexec_b64 s[0:1], vcc
	global_store_dwordx4 v[204:205], v[196:199], off
	global_store_dwordx4 v[204:205], v[200:203], off offset:64
	s_or_b64 exec, exec, s[0:1]
	s_mov_b64 s[10:11], exec
	s_branch .LBB0_907
.Ll2e_bf16:
	v_add_f32_e32 v126, v126, v210
	v_add_f32_e32 v127, v127, v211
	v_add_f32_e32 v128, v128, v212
	v_add_f32_e32 v129, v129, v213
	v_mul_f32_e32 v126, 0xbfb8aa3b, v126
	v_mul_f32_e32 v127, 0xbfb8aa3b, v127
	v_mul_f32_e32 v128, 0xbfb8aa3b, v128
	v_mul_f32_e32 v129, 0xbfb8aa3b, v129
	v_exp_f32_e32 v126, v126
	v_exp_f32_e32 v127, v127
	v_exp_f32_e32 v128, v128
	v_exp_f32_e32 v129, v129
	s_nop 0
	v_add_f32_e32 v126, 1.0, v126
	v_add_f32_e32 v127, 1.0, v127
	v_add_f32_e32 v128, 1.0, v128
	v_add_f32_e32 v129, 1.0, v129
	v_rcp_f32_e32 v226, v126
	v_rcp_f32_e32 v227, v127
	v_rcp_f32_e32 v228, v128
	v_rcp_f32_e32 v229, v129
	s_nop 0
	v_fma_f32 v126, -v126, v226, 1.0
	v_fma_f32 v127, -v127, v227, 1.0
	v_fma_f32 v128, -v128, v228, 1.0
	v_fma_f32 v129, -v129, v229, 1.0
	v_fma_f32 v126, v126, v226, v226
	v_fma_f32 v127, v127, v227, v227
	v_fma_f32 v128, v128, v228, v228
	v_fma_f32 v129, v129, v229, v229
	v_add_f32_e32 v122, v122, v214
	v_add_f32_e32 v123, v123, v215
	v_add_f32_e32 v124, v124, v216
	v_add_f32_e32 v125, v125, v217
	v_mul_f32_e32 v122, 0xbfb8aa3b, v122
	v_mul_f32_e32 v123, 0xbfb8aa3b, v123
	v_mul_f32_e32 v124, 0xbfb8aa3b, v124
	v_mul_f32_e32 v125, 0xbfb8aa3b, v125
	v_exp_f32_e32 v122, v122
	v_exp_f32_e32 v123, v123
	v_exp_f32_e32 v124, v124
	v_exp_f32_e32 v125, v125
	s_nop 0
	v_add_f32_e32 v122, 1.0, v122
	v_add_f32_e32 v123, 1.0, v123
	v_add_f32_e32 v124, 1.0, v124
	v_add_f32_e32 v125, 1.0, v125
	v_rcp_f32_e32 v226, v122
	v_rcp_f32_e32 v227, v123
	v_rcp_f32_e32 v228, v124
	v_rcp_f32_e32 v229, v125
	s_nop 0
	v_fma_f32 v122, -v122, v226, 1.0
	v_fma_f32 v123, -v123, v227, 1.0
	v_fma_f32 v124, -v124, v228, 1.0
	v_fma_f32 v125, -v125, v229, 1.0
	v_fma_f32 v122, v122, v226, v226
	v_fma_f32 v123, v123, v227, v227
	v_fma_f32 v124, v124, v228, v228
	v_fma_f32 v125, v125, v229, v229
	v_add_f32_e32 v118, v118, v218
	v_add_f32_e32 v119, v119, v219
	v_add_f32_e32 v120, v120, v220
	v_add_f32_e32 v121, v121, v221
	v_mul_f32_e32 v118, 0xbfb8aa3b, v118
	v_mul_f32_e32 v119, 0xbfb8aa3b, v119
	v_mul_f32_e32 v120, 0xbfb8aa3b, v120
	v_mul_f32_e32 v121, 0xbfb8aa3b, v121
	v_exp_f32_e32 v118, v118
	v_exp_f32_e32 v119, v119
	v_exp_f32_e32 v120, v120
	v_exp_f32_e32 v121, v121
	s_nop 0
	v_add_f32_e32 v118, 1.0, v118
	v_add_f32_e32 v119, 1.0, v119
	v_add_f32_e32 v120, 1.0, v120
	v_add_f32_e32 v121, 1.0, v121
	v_rcp_f32_e32 v226, v118
	v_rcp_f32_e32 v227, v119
	v_rcp_f32_e32 v228, v120
	v_rcp_f32_e32 v229, v121
	s_nop 0
	v_fma_f32 v118, -v118, v226, 1.0
	v_fma_f32 v119, -v119, v227, 1.0
	v_fma_f32 v120, -v120, v228, 1.0
	v_fma_f32 v121, -v121, v229, 1.0
	v_fma_f32 v118, v118, v226, v226
	v_fma_f32 v119, v119, v227, v227
	v_fma_f32 v120, v120, v228, v228
	v_fma_f32 v121, v121, v229, v229
	v_add_f32_e32 v114, v114, v222
	v_add_f32_e32 v115, v115, v223
	v_add_f32_e32 v116, v116, v224
	v_add_f32_e32 v117, v117, v225
	v_mul_f32_e32 v114, 0xbfb8aa3b, v114
	v_mul_f32_e32 v115, 0xbfb8aa3b, v115
	v_mul_f32_e32 v116, 0xbfb8aa3b, v116
	v_mul_f32_e32 v117, 0xbfb8aa3b, v117
	v_exp_f32_e32 v114, v114
	v_exp_f32_e32 v115, v115
	v_exp_f32_e32 v116, v116
	v_exp_f32_e32 v117, v117
	s_nop 0
	v_add_f32_e32 v114, 1.0, v114
	v_add_f32_e32 v115, 1.0, v115
	v_add_f32_e32 v116, 1.0, v116
	v_add_f32_e32 v117, 1.0, v117
	v_rcp_f32_e32 v226, v114
	v_rcp_f32_e32 v227, v115
	v_rcp_f32_e32 v228, v116
	v_rcp_f32_e32 v229, v117
	s_nop 0
	v_fma_f32 v114, -v114, v226, 1.0
	v_fma_f32 v115, -v115, v227, 1.0
	v_fma_f32 v116, -v116, v228, 1.0
	v_fma_f32 v117, -v117, v229, 1.0
	v_fma_f32 v114, v114, v226, v226
	v_fma_f32 v115, v115, v227, v227
	v_fma_f32 v116, v116, v228, v228
	v_fma_f32 v117, v117, v229, v229
	v_cvt_pk_bf16_f32 v196, v126, v127
	v_cvt_pk_bf16_f32 v197, v128, v129
	v_cvt_pk_bf16_f32 v198, v122, v123
	v_cvt_pk_bf16_f32 v199, v124, v125
	v_cvt_pk_bf16_f32 v200, v118, v119
	v_cvt_pk_bf16_f32 v201, v120, v121
	v_cvt_pk_bf16_f32 v202, v114, v115
	v_cvt_pk_bf16_f32 v203, v116, v117
	v_cmp_gt_i32_e32 vcc, s38, v206
	s_nop 0
	v_permlane16_swap_b32_e32 v196, v198
	v_permlane16_swap_b32_e32 v197, v199
	v_permlane16_swap_b32_e32 v200, v202
	v_permlane16_swap_b32_e32 v201, v203
	s_and_saveexec_b64 s[0:1], vcc
	global_store_dwordx4 v[204:205], v[196:199], off
	global_store_dwordx4 v[204:205], v[200:203], off offset:64
	s_or_b64 exec, exec, s[0:1]
	v_lshl_add_u64 v[204:205], v[204:205], 0, v[208:209]
	v_add_u32_e32 v206, 16, v206
	v_add_f32_e32 v110, v110, v210
	v_add_f32_e32 v111, v111, v211
	v_add_f32_e32 v112, v112, v212
	v_add_f32_e32 v113, v113, v213
	v_mul_f32_e32 v110, 0xbfb8aa3b, v110
	v_mul_f32_e32 v111, 0xbfb8aa3b, v111
	v_mul_f32_e32 v112, 0xbfb8aa3b, v112
	v_mul_f32_e32 v113, 0xbfb8aa3b, v113
	v_exp_f32_e32 v110, v110
	v_exp_f32_e32 v111, v111
	v_exp_f32_e32 v112, v112
	v_exp_f32_e32 v113, v113
	s_nop 0
	v_add_f32_e32 v110, 1.0, v110
	v_add_f32_e32 v111, 1.0, v111
	v_add_f32_e32 v112, 1.0, v112
	v_add_f32_e32 v113, 1.0, v113
	v_rcp_f32_e32 v226, v110
	v_rcp_f32_e32 v227, v111
	v_rcp_f32_e32 v228, v112
	v_rcp_f32_e32 v229, v113
	s_nop 0
	v_fma_f32 v110, -v110, v226, 1.0
	v_fma_f32 v111, -v111, v227, 1.0
	v_fma_f32 v112, -v112, v228, 1.0
	v_fma_f32 v113, -v113, v229, 1.0
	v_fma_f32 v110, v110, v226, v226
	v_fma_f32 v111, v111, v227, v227
	v_fma_f32 v112, v112, v228, v228
	v_fma_f32 v113, v113, v229, v229
	v_add_f32_e32 v106, v106, v214
	v_add_f32_e32 v107, v107, v215
	v_add_f32_e32 v108, v108, v216
	v_add_f32_e32 v109, v109, v217
	v_mul_f32_e32 v106, 0xbfb8aa3b, v106
	v_mul_f32_e32 v107, 0xbfb8aa3b, v107
	v_mul_f32_e32 v108, 0xbfb8aa3b, v108
	v_mul_f32_e32 v109, 0xbfb8aa3b, v109
	v_exp_f32_e32 v106, v106
	v_exp_f32_e32 v107, v107
	v_exp_f32_e32 v108, v108
	v_exp_f32_e32 v109, v109
	s_nop 0
	v_add_f32_e32 v106, 1.0, v106
	v_add_f32_e32 v107, 1.0, v107
	v_add_f32_e32 v108, 1.0, v108
	v_add_f32_e32 v109, 1.0, v109
	v_rcp_f32_e32 v226, v106
	v_rcp_f32_e32 v227, v107
	v_rcp_f32_e32 v228, v108
	v_rcp_f32_e32 v229, v109
	s_nop 0
	v_fma_f32 v106, -v106, v226, 1.0
	v_fma_f32 v107, -v107, v227, 1.0
	v_fma_f32 v108, -v108, v228, 1.0
	v_fma_f32 v109, -v109, v229, 1.0
	v_fma_f32 v106, v106, v226, v226
	v_fma_f32 v107, v107, v227, v227
	v_fma_f32 v108, v108, v228, v228
	v_fma_f32 v109, v109, v229, v229
	v_add_f32_e32 v102, v102, v218
	v_add_f32_e32 v103, v103, v219
	v_add_f32_e32 v104, v104, v220
	v_add_f32_e32 v105, v105, v221
	v_mul_f32_e32 v102, 0xbfb8aa3b, v102
	v_mul_f32_e32 v103, 0xbfb8aa3b, v103
	v_mul_f32_e32 v104, 0xbfb8aa3b, v104
	v_mul_f32_e32 v105, 0xbfb8aa3b, v105
	v_exp_f32_e32 v102, v102
	v_exp_f32_e32 v103, v103
	v_exp_f32_e32 v104, v104
	v_exp_f32_e32 v105, v105
	s_nop 0
	v_add_f32_e32 v102, 1.0, v102
	v_add_f32_e32 v103, 1.0, v103
	v_add_f32_e32 v104, 1.0, v104
	v_add_f32_e32 v105, 1.0, v105
	v_rcp_f32_e32 v226, v102
	v_rcp_f32_e32 v227, v103
	v_rcp_f32_e32 v228, v104
	v_rcp_f32_e32 v229, v105
	s_nop 0
	v_fma_f32 v102, -v102, v226, 1.0
	v_fma_f32 v103, -v103, v227, 1.0
	v_fma_f32 v104, -v104, v228, 1.0
	v_fma_f32 v105, -v105, v229, 1.0
	v_fma_f32 v102, v102, v226, v226
	v_fma_f32 v103, v103, v227, v227
	v_fma_f32 v104, v104, v228, v228
	v_fma_f32 v105, v105, v229, v229
	v_add_f32_e32 v98, v98, v222
	v_add_f32_e32 v99, v99, v223
	v_add_f32_e32 v100, v100, v224
	v_add_f32_e32 v101, v101, v225
	v_mul_f32_e32 v98, 0xbfb8aa3b, v98
	v_mul_f32_e32 v99, 0xbfb8aa3b, v99
	v_mul_f32_e32 v100, 0xbfb8aa3b, v100
	v_mul_f32_e32 v101, 0xbfb8aa3b, v101
	v_exp_f32_e32 v98, v98
	v_exp_f32_e32 v99, v99
	v_exp_f32_e32 v100, v100
	v_exp_f32_e32 v101, v101
	s_nop 0
	v_add_f32_e32 v98, 1.0, v98
	v_add_f32_e32 v99, 1.0, v99
	v_add_f32_e32 v100, 1.0, v100
	v_add_f32_e32 v101, 1.0, v101
	v_rcp_f32_e32 v226, v98
	v_rcp_f32_e32 v227, v99
	v_rcp_f32_e32 v228, v100
	v_rcp_f32_e32 v229, v101
	s_nop 0
	v_fma_f32 v98, -v98, v226, 1.0
	v_fma_f32 v99, -v99, v227, 1.0
	v_fma_f32 v100, -v100, v228, 1.0
	v_fma_f32 v101, -v101, v229, 1.0
	v_fma_f32 v98, v98, v226, v226
	v_fma_f32 v99, v99, v227, v227
	v_fma_f32 v100, v100, v228, v228
	v_fma_f32 v101, v101, v229, v229
	v_cvt_pk_bf16_f32 v196, v110, v111
	v_cvt_pk_bf16_f32 v197, v112, v113
	v_cvt_pk_bf16_f32 v198, v106, v107
	v_cvt_pk_bf16_f32 v199, v108, v109
	v_cvt_pk_bf16_f32 v200, v102, v103
	v_cvt_pk_bf16_f32 v201, v104, v105
	v_cvt_pk_bf16_f32 v202, v98, v99
	v_cvt_pk_bf16_f32 v203, v100, v101
	v_cmp_gt_i32_e32 vcc, s38, v206
	s_nop 0
	v_permlane16_swap_b32_e32 v196, v198
	v_permlane16_swap_b32_e32 v197, v199
	v_permlane16_swap_b32_e32 v200, v202
	v_permlane16_swap_b32_e32 v201, v203
	s_and_saveexec_b64 s[0:1], vcc
	global_store_dwordx4 v[204:205], v[196:199], off
	global_store_dwordx4 v[204:205], v[200:203], off offset:64
	s_or_b64 exec, exec, s[0:1]
	v_lshl_add_u64 v[204:205], v[204:205], 0, v[208:209]
	v_add_u32_e32 v206, 16, v206
	v_add_f32_e32 v94, v94, v210
	v_add_f32_e32 v95, v95, v211
	v_add_f32_e32 v96, v96, v212
	v_add_f32_e32 v97, v97, v213
	v_mul_f32_e32 v94, 0xbfb8aa3b, v94
	v_mul_f32_e32 v95, 0xbfb8aa3b, v95
	v_mul_f32_e32 v96, 0xbfb8aa3b, v96
	v_mul_f32_e32 v97, 0xbfb8aa3b, v97
	v_exp_f32_e32 v94, v94
	v_exp_f32_e32 v95, v95
	v_exp_f32_e32 v96, v96
	v_exp_f32_e32 v97, v97
	s_nop 0
	v_add_f32_e32 v94, 1.0, v94
	v_add_f32_e32 v95, 1.0, v95
	v_add_f32_e32 v96, 1.0, v96
	v_add_f32_e32 v97, 1.0, v97
	v_rcp_f32_e32 v226, v94
	v_rcp_f32_e32 v227, v95
	v_rcp_f32_e32 v228, v96
	v_rcp_f32_e32 v229, v97
	s_nop 0
	v_fma_f32 v94, -v94, v226, 1.0
	v_fma_f32 v95, -v95, v227, 1.0
	v_fma_f32 v96, -v96, v228, 1.0
	v_fma_f32 v97, -v97, v229, 1.0
	v_fma_f32 v94, v94, v226, v226
	v_fma_f32 v95, v95, v227, v227
	v_fma_f32 v96, v96, v228, v228
	v_fma_f32 v97, v97, v229, v229
	v_add_f32_e32 v90, v90, v214
	v_add_f32_e32 v91, v91, v215
	v_add_f32_e32 v92, v92, v216
	v_add_f32_e32 v93, v93, v217
	v_mul_f32_e32 v90, 0xbfb8aa3b, v90
	v_mul_f32_e32 v91, 0xbfb8aa3b, v91
	v_mul_f32_e32 v92, 0xbfb8aa3b, v92
	v_mul_f32_e32 v93, 0xbfb8aa3b, v93
	v_exp_f32_e32 v90, v90
	v_exp_f32_e32 v91, v91
	v_exp_f32_e32 v92, v92
	v_exp_f32_e32 v93, v93
	s_nop 0
	v_add_f32_e32 v90, 1.0, v90
	v_add_f32_e32 v91, 1.0, v91
	v_add_f32_e32 v92, 1.0, v92
	v_add_f32_e32 v93, 1.0, v93
	v_rcp_f32_e32 v226, v90
	v_rcp_f32_e32 v227, v91
	v_rcp_f32_e32 v228, v92
	v_rcp_f32_e32 v229, v93
	s_nop 0
	v_fma_f32 v90, -v90, v226, 1.0
	v_fma_f32 v91, -v91, v227, 1.0
	v_fma_f32 v92, -v92, v228, 1.0
	v_fma_f32 v93, -v93, v229, 1.0
	v_fma_f32 v90, v90, v226, v226
	v_fma_f32 v91, v91, v227, v227
	v_fma_f32 v92, v92, v228, v228
	v_fma_f32 v93, v93, v229, v229
	v_add_f32_e32 v86, v86, v218
	v_add_f32_e32 v87, v87, v219
	v_add_f32_e32 v88, v88, v220
	v_add_f32_e32 v89, v89, v221
	v_mul_f32_e32 v86, 0xbfb8aa3b, v86
	v_mul_f32_e32 v87, 0xbfb8aa3b, v87
	v_mul_f32_e32 v88, 0xbfb8aa3b, v88
	v_mul_f32_e32 v89, 0xbfb8aa3b, v89
	v_exp_f32_e32 v86, v86
	v_exp_f32_e32 v87, v87
	v_exp_f32_e32 v88, v88
	v_exp_f32_e32 v89, v89
	s_nop 0
	v_add_f32_e32 v86, 1.0, v86
	v_add_f32_e32 v87, 1.0, v87
	v_add_f32_e32 v88, 1.0, v88
	v_add_f32_e32 v89, 1.0, v89
	v_rcp_f32_e32 v226, v86
	v_rcp_f32_e32 v227, v87
	v_rcp_f32_e32 v228, v88
	v_rcp_f32_e32 v229, v89
	s_nop 0
	v_fma_f32 v86, -v86, v226, 1.0
	v_fma_f32 v87, -v87, v227, 1.0
	v_fma_f32 v88, -v88, v228, 1.0
	v_fma_f32 v89, -v89, v229, 1.0
	v_fma_f32 v86, v86, v226, v226
	v_fma_f32 v87, v87, v227, v227
	v_fma_f32 v88, v88, v228, v228
	v_fma_f32 v89, v89, v229, v229
	v_add_f32_e32 v82, v82, v222
	v_add_f32_e32 v83, v83, v223
	v_add_f32_e32 v84, v84, v224
	v_add_f32_e32 v85, v85, v225
	v_mul_f32_e32 v82, 0xbfb8aa3b, v82
	v_mul_f32_e32 v83, 0xbfb8aa3b, v83
	v_mul_f32_e32 v84, 0xbfb8aa3b, v84
	v_mul_f32_e32 v85, 0xbfb8aa3b, v85
	v_exp_f32_e32 v82, v82
	v_exp_f32_e32 v83, v83
	v_exp_f32_e32 v84, v84
	v_exp_f32_e32 v85, v85
	s_nop 0
	v_add_f32_e32 v82, 1.0, v82
	v_add_f32_e32 v83, 1.0, v83
	v_add_f32_e32 v84, 1.0, v84
	v_add_f32_e32 v85, 1.0, v85
	v_rcp_f32_e32 v226, v82
	v_rcp_f32_e32 v227, v83
	v_rcp_f32_e32 v228, v84
	v_rcp_f32_e32 v229, v85
	s_nop 0
	v_fma_f32 v82, -v82, v226, 1.0
	v_fma_f32 v83, -v83, v227, 1.0
	v_fma_f32 v84, -v84, v228, 1.0
	v_fma_f32 v85, -v85, v229, 1.0
	v_fma_f32 v82, v82, v226, v226
	v_fma_f32 v83, v83, v227, v227
	v_fma_f32 v84, v84, v228, v228
	v_fma_f32 v85, v85, v229, v229
	v_cvt_pk_bf16_f32 v196, v94, v95
	v_cvt_pk_bf16_f32 v197, v96, v97
	v_cvt_pk_bf16_f32 v198, v90, v91
	v_cvt_pk_bf16_f32 v199, v92, v93
	v_cvt_pk_bf16_f32 v200, v86, v87
	v_cvt_pk_bf16_f32 v201, v88, v89
	v_cvt_pk_bf16_f32 v202, v82, v83
	v_cvt_pk_bf16_f32 v203, v84, v85
	v_cmp_gt_i32_e32 vcc, s38, v206
	s_nop 0
	v_permlane16_swap_b32_e32 v196, v198
	v_permlane16_swap_b32_e32 v197, v199
	v_permlane16_swap_b32_e32 v200, v202
	v_permlane16_swap_b32_e32 v201, v203
	s_and_saveexec_b64 s[0:1], vcc
	global_store_dwordx4 v[204:205], v[196:199], off
	global_store_dwordx4 v[204:205], v[200:203], off offset:64
	s_or_b64 exec, exec, s[0:1]
	v_lshl_add_u64 v[204:205], v[204:205], 0, v[208:209]
	v_add_u32_e32 v206, 16, v206
	v_add_f32_e32 v78, v78, v210
	v_add_f32_e32 v79, v79, v211
	v_add_f32_e32 v80, v80, v212
	v_add_f32_e32 v81, v81, v213
	v_mul_f32_e32 v78, 0xbfb8aa3b, v78
	v_mul_f32_e32 v79, 0xbfb8aa3b, v79
	v_mul_f32_e32 v80, 0xbfb8aa3b, v80
	v_mul_f32_e32 v81, 0xbfb8aa3b, v81
	v_exp_f32_e32 v78, v78
	v_exp_f32_e32 v79, v79
	v_exp_f32_e32 v80, v80
	v_exp_f32_e32 v81, v81
	s_nop 0
	v_add_f32_e32 v78, 1.0, v78
	v_add_f32_e32 v79, 1.0, v79
	v_add_f32_e32 v80, 1.0, v80
	v_add_f32_e32 v81, 1.0, v81
	v_rcp_f32_e32 v226, v78
	v_rcp_f32_e32 v227, v79
	v_rcp_f32_e32 v228, v80
	v_rcp_f32_e32 v229, v81
	s_nop 0
	v_fma_f32 v78, -v78, v226, 1.0
	v_fma_f32 v79, -v79, v227, 1.0
	v_fma_f32 v80, -v80, v228, 1.0
	v_fma_f32 v81, -v81, v229, 1.0
	v_fma_f32 v78, v78, v226, v226
	v_fma_f32 v79, v79, v227, v227
	v_fma_f32 v80, v80, v228, v228
	v_fma_f32 v81, v81, v229, v229
	v_add_f32_e32 v74, v74, v214
	v_add_f32_e32 v75, v75, v215
	v_add_f32_e32 v76, v76, v216
	v_add_f32_e32 v77, v77, v217
	v_mul_f32_e32 v74, 0xbfb8aa3b, v74
	v_mul_f32_e32 v75, 0xbfb8aa3b, v75
	v_mul_f32_e32 v76, 0xbfb8aa3b, v76
	v_mul_f32_e32 v77, 0xbfb8aa3b, v77
	v_exp_f32_e32 v74, v74
	v_exp_f32_e32 v75, v75
	v_exp_f32_e32 v76, v76
	v_exp_f32_e32 v77, v77
	s_nop 0
	v_add_f32_e32 v74, 1.0, v74
	v_add_f32_e32 v75, 1.0, v75
	v_add_f32_e32 v76, 1.0, v76
	v_add_f32_e32 v77, 1.0, v77
	v_rcp_f32_e32 v226, v74
	v_rcp_f32_e32 v227, v75
	v_rcp_f32_e32 v228, v76
	v_rcp_f32_e32 v229, v77
	s_nop 0
	v_fma_f32 v74, -v74, v226, 1.0
	v_fma_f32 v75, -v75, v227, 1.0
	v_fma_f32 v76, -v76, v228, 1.0
	v_fma_f32 v77, -v77, v229, 1.0
	v_fma_f32 v74, v74, v226, v226
	v_fma_f32 v75, v75, v227, v227
	v_fma_f32 v76, v76, v228, v228
	v_fma_f32 v77, v77, v229, v229
	v_add_f32_e32 v70, v70, v218
	v_add_f32_e32 v71, v71, v219
	v_add_f32_e32 v72, v72, v220
	v_add_f32_e32 v73, v73, v221
	v_mul_f32_e32 v70, 0xbfb8aa3b, v70
	v_mul_f32_e32 v71, 0xbfb8aa3b, v71
	v_mul_f32_e32 v72, 0xbfb8aa3b, v72
	v_mul_f32_e32 v73, 0xbfb8aa3b, v73
	v_exp_f32_e32 v70, v70
	v_exp_f32_e32 v71, v71
	v_exp_f32_e32 v72, v72
	v_exp_f32_e32 v73, v73
	s_nop 0
	v_add_f32_e32 v70, 1.0, v70
	v_add_f32_e32 v71, 1.0, v71
	v_add_f32_e32 v72, 1.0, v72
	v_add_f32_e32 v73, 1.0, v73
	v_rcp_f32_e32 v226, v70
	v_rcp_f32_e32 v227, v71
	v_rcp_f32_e32 v228, v72
	v_rcp_f32_e32 v229, v73
	s_nop 0
	v_fma_f32 v70, -v70, v226, 1.0
	v_fma_f32 v71, -v71, v227, 1.0
	v_fma_f32 v72, -v72, v228, 1.0
	v_fma_f32 v73, -v73, v229, 1.0
	v_fma_f32 v70, v70, v226, v226
	v_fma_f32 v71, v71, v227, v227
	v_fma_f32 v72, v72, v228, v228
	v_fma_f32 v73, v73, v229, v229
	v_add_f32_e32 v66, v66, v222
	v_add_f32_e32 v67, v67, v223
	v_add_f32_e32 v68, v68, v224
	v_add_f32_e32 v69, v69, v225
	v_mul_f32_e32 v66, 0xbfb8aa3b, v66
	v_mul_f32_e32 v67, 0xbfb8aa3b, v67
	v_mul_f32_e32 v68, 0xbfb8aa3b, v68
	v_mul_f32_e32 v69, 0xbfb8aa3b, v69
	v_exp_f32_e32 v66, v66
	v_exp_f32_e32 v67, v67
	v_exp_f32_e32 v68, v68
	v_exp_f32_e32 v69, v69
	s_nop 0
	v_add_f32_e32 v66, 1.0, v66
	v_add_f32_e32 v67, 1.0, v67
	v_add_f32_e32 v68, 1.0, v68
	v_add_f32_e32 v69, 1.0, v69
	v_rcp_f32_e32 v226, v66
	v_rcp_f32_e32 v227, v67
	v_rcp_f32_e32 v228, v68
	v_rcp_f32_e32 v229, v69
	s_nop 0
	v_fma_f32 v66, -v66, v226, 1.0
	v_fma_f32 v67, -v67, v227, 1.0
	v_fma_f32 v68, -v68, v228, 1.0
	v_fma_f32 v69, -v69, v229, 1.0
	v_fma_f32 v66, v66, v226, v226
	v_fma_f32 v67, v67, v227, v227
	v_fma_f32 v68, v68, v228, v228
	v_fma_f32 v69, v69, v229, v229
	v_cvt_pk_bf16_f32 v196, v78, v79
	v_cvt_pk_bf16_f32 v197, v80, v81
	v_cvt_pk_bf16_f32 v198, v74, v75
	v_cvt_pk_bf16_f32 v199, v76, v77
	v_cvt_pk_bf16_f32 v200, v70, v71
	v_cvt_pk_bf16_f32 v201, v72, v73
	v_cvt_pk_bf16_f32 v202, v66, v67
	v_cvt_pk_bf16_f32 v203, v68, v69
	v_cmp_gt_i32_e32 vcc, s38, v206
	s_nop 0
	v_permlane16_swap_b32_e32 v196, v198
	v_permlane16_swap_b32_e32 v197, v199
	v_permlane16_swap_b32_e32 v200, v202
	v_permlane16_swap_b32_e32 v201, v203
	s_and_saveexec_b64 s[0:1], vcc
	global_store_dwordx4 v[204:205], v[196:199], off
	global_store_dwordx4 v[204:205], v[200:203], off offset:64
	s_or_b64 exec, exec, s[0:1]
	v_lshl_add_u64 v[204:205], v[204:205], 0, v[208:209]
	v_add_u32_e32 v206, 16, v206
	v_add_f32_e32 v62, v62, v210
	v_add_f32_e32 v63, v63, v211
	v_add_f32_e32 v64, v64, v212
	v_add_f32_e32 v65, v65, v213
	v_mul_f32_e32 v62, 0xbfb8aa3b, v62
	v_mul_f32_e32 v63, 0xbfb8aa3b, v63
	v_mul_f32_e32 v64, 0xbfb8aa3b, v64
	v_mul_f32_e32 v65, 0xbfb8aa3b, v65
	v_exp_f32_e32 v62, v62
	v_exp_f32_e32 v63, v63
	v_exp_f32_e32 v64, v64
	v_exp_f32_e32 v65, v65
	s_nop 0
	v_add_f32_e32 v62, 1.0, v62
	v_add_f32_e32 v63, 1.0, v63
	v_add_f32_e32 v64, 1.0, v64
	v_add_f32_e32 v65, 1.0, v65
	v_rcp_f32_e32 v226, v62
	v_rcp_f32_e32 v227, v63
	v_rcp_f32_e32 v228, v64
	v_rcp_f32_e32 v229, v65
	s_nop 0
	v_fma_f32 v62, -v62, v226, 1.0
	v_fma_f32 v63, -v63, v227, 1.0
	v_fma_f32 v64, -v64, v228, 1.0
	v_fma_f32 v65, -v65, v229, 1.0
	v_fma_f32 v62, v62, v226, v226
	v_fma_f32 v63, v63, v227, v227
	v_fma_f32 v64, v64, v228, v228
	v_fma_f32 v65, v65, v229, v229
	v_add_f32_e32 v58, v58, v214
	v_add_f32_e32 v59, v59, v215
	v_add_f32_e32 v60, v60, v216
	v_add_f32_e32 v61, v61, v217
	v_mul_f32_e32 v58, 0xbfb8aa3b, v58
	v_mul_f32_e32 v59, 0xbfb8aa3b, v59
	v_mul_f32_e32 v60, 0xbfb8aa3b, v60
	v_mul_f32_e32 v61, 0xbfb8aa3b, v61
	v_exp_f32_e32 v58, v58
	v_exp_f32_e32 v59, v59
	v_exp_f32_e32 v60, v60
	v_exp_f32_e32 v61, v61
	s_nop 0
	v_add_f32_e32 v58, 1.0, v58
	v_add_f32_e32 v59, 1.0, v59
	v_add_f32_e32 v60, 1.0, v60
	v_add_f32_e32 v61, 1.0, v61
	v_rcp_f32_e32 v226, v58
	v_rcp_f32_e32 v227, v59
	v_rcp_f32_e32 v228, v60
	v_rcp_f32_e32 v229, v61
	s_nop 0
	v_fma_f32 v58, -v58, v226, 1.0
	v_fma_f32 v59, -v59, v227, 1.0
	v_fma_f32 v60, -v60, v228, 1.0
	v_fma_f32 v61, -v61, v229, 1.0
	v_fma_f32 v58, v58, v226, v226
	v_fma_f32 v59, v59, v227, v227
	v_fma_f32 v60, v60, v228, v228
	v_fma_f32 v61, v61, v229, v229
	v_add_f32_e32 v54, v54, v218
	v_add_f32_e32 v55, v55, v219
	v_add_f32_e32 v56, v56, v220
	v_add_f32_e32 v57, v57, v221
	v_mul_f32_e32 v54, 0xbfb8aa3b, v54
	v_mul_f32_e32 v55, 0xbfb8aa3b, v55
	v_mul_f32_e32 v56, 0xbfb8aa3b, v56
	v_mul_f32_e32 v57, 0xbfb8aa3b, v57
	v_exp_f32_e32 v54, v54
	v_exp_f32_e32 v55, v55
	v_exp_f32_e32 v56, v56
	v_exp_f32_e32 v57, v57
	s_nop 0
	v_add_f32_e32 v54, 1.0, v54
	v_add_f32_e32 v55, 1.0, v55
	v_add_f32_e32 v56, 1.0, v56
	v_add_f32_e32 v57, 1.0, v57
	v_rcp_f32_e32 v226, v54
	v_rcp_f32_e32 v227, v55
	v_rcp_f32_e32 v228, v56
	v_rcp_f32_e32 v229, v57
	s_nop 0
	v_fma_f32 v54, -v54, v226, 1.0
	v_fma_f32 v55, -v55, v227, 1.0
	v_fma_f32 v56, -v56, v228, 1.0
	v_fma_f32 v57, -v57, v229, 1.0
	v_fma_f32 v54, v54, v226, v226
	v_fma_f32 v55, v55, v227, v227
	v_fma_f32 v56, v56, v228, v228
	v_fma_f32 v57, v57, v229, v229
	v_add_f32_e32 v50, v50, v222
	v_add_f32_e32 v51, v51, v223
	v_add_f32_e32 v52, v52, v224
	v_add_f32_e32 v53, v53, v225
	v_mul_f32_e32 v50, 0xbfb8aa3b, v50
	v_mul_f32_e32 v51, 0xbfb8aa3b, v51
	v_mul_f32_e32 v52, 0xbfb8aa3b, v52
	v_mul_f32_e32 v53, 0xbfb8aa3b, v53
	v_exp_f32_e32 v50, v50
	v_exp_f32_e32 v51, v51
	v_exp_f32_e32 v52, v52
	v_exp_f32_e32 v53, v53
	s_nop 0
	v_add_f32_e32 v50, 1.0, v50
	v_add_f32_e32 v51, 1.0, v51
	v_add_f32_e32 v52, 1.0, v52
	v_add_f32_e32 v53, 1.0, v53
	v_rcp_f32_e32 v226, v50
	v_rcp_f32_e32 v227, v51
	v_rcp_f32_e32 v228, v52
	v_rcp_f32_e32 v229, v53
	s_nop 0
	v_fma_f32 v50, -v50, v226, 1.0
	v_fma_f32 v51, -v51, v227, 1.0
	v_fma_f32 v52, -v52, v228, 1.0
	v_fma_f32 v53, -v53, v229, 1.0
	v_fma_f32 v50, v50, v226, v226
	v_fma_f32 v51, v51, v227, v227
	v_fma_f32 v52, v52, v228, v228
	v_fma_f32 v53, v53, v229, v229
	v_cvt_pk_bf16_f32 v196, v62, v63
	v_cvt_pk_bf16_f32 v197, v64, v65
	v_cvt_pk_bf16_f32 v198, v58, v59
	v_cvt_pk_bf16_f32 v199, v60, v61
	v_cvt_pk_bf16_f32 v200, v54, v55
	v_cvt_pk_bf16_f32 v201, v56, v57
	v_cvt_pk_bf16_f32 v202, v50, v51
	v_cvt_pk_bf16_f32 v203, v52, v53
	v_cmp_gt_i32_e32 vcc, s38, v206
	s_nop 0
	v_permlane16_swap_b32_e32 v196, v198
	v_permlane16_swap_b32_e32 v197, v199
	v_permlane16_swap_b32_e32 v200, v202
	v_permlane16_swap_b32_e32 v201, v203
	s_and_saveexec_b64 s[0:1], vcc
	global_store_dwordx4 v[204:205], v[196:199], off
	global_store_dwordx4 v[204:205], v[200:203], off offset:64
	s_or_b64 exec, exec, s[0:1]
	v_lshl_add_u64 v[204:205], v[204:205], 0, v[208:209]
	v_add_u32_e32 v206, 16, v206
	v_add_f32_e32 v46, v46, v210
	v_add_f32_e32 v47, v47, v211
	v_add_f32_e32 v48, v48, v212
	v_add_f32_e32 v49, v49, v213
	v_mul_f32_e32 v46, 0xbfb8aa3b, v46
	v_mul_f32_e32 v47, 0xbfb8aa3b, v47
	v_mul_f32_e32 v48, 0xbfb8aa3b, v48
	v_mul_f32_e32 v49, 0xbfb8aa3b, v49
	v_exp_f32_e32 v46, v46
	v_exp_f32_e32 v47, v47
	v_exp_f32_e32 v48, v48
	v_exp_f32_e32 v49, v49
	s_nop 0
	v_add_f32_e32 v46, 1.0, v46
	v_add_f32_e32 v47, 1.0, v47
	v_add_f32_e32 v48, 1.0, v48
	v_add_f32_e32 v49, 1.0, v49
	v_rcp_f32_e32 v226, v46
	v_rcp_f32_e32 v227, v47
	v_rcp_f32_e32 v228, v48
	v_rcp_f32_e32 v229, v49
	s_nop 0
	v_fma_f32 v46, -v46, v226, 1.0
	v_fma_f32 v47, -v47, v227, 1.0
	v_fma_f32 v48, -v48, v228, 1.0
	v_fma_f32 v49, -v49, v229, 1.0
	v_fma_f32 v46, v46, v226, v226
	v_fma_f32 v47, v47, v227, v227
	v_fma_f32 v48, v48, v228, v228
	v_fma_f32 v49, v49, v229, v229
	v_add_f32_e32 v42, v42, v214
	v_add_f32_e32 v43, v43, v215
	v_add_f32_e32 v44, v44, v216
	v_add_f32_e32 v45, v45, v217
	v_mul_f32_e32 v42, 0xbfb8aa3b, v42
	v_mul_f32_e32 v43, 0xbfb8aa3b, v43
	v_mul_f32_e32 v44, 0xbfb8aa3b, v44
	v_mul_f32_e32 v45, 0xbfb8aa3b, v45
	v_exp_f32_e32 v42, v42
	v_exp_f32_e32 v43, v43
	v_exp_f32_e32 v44, v44
	v_exp_f32_e32 v45, v45
	s_nop 0
	v_add_f32_e32 v42, 1.0, v42
	v_add_f32_e32 v43, 1.0, v43
	v_add_f32_e32 v44, 1.0, v44
	v_add_f32_e32 v45, 1.0, v45
	v_rcp_f32_e32 v226, v42
	v_rcp_f32_e32 v227, v43
	v_rcp_f32_e32 v228, v44
	v_rcp_f32_e32 v229, v45
	s_nop 0
	v_fma_f32 v42, -v42, v226, 1.0
	v_fma_f32 v43, -v43, v227, 1.0
	v_fma_f32 v44, -v44, v228, 1.0
	v_fma_f32 v45, -v45, v229, 1.0
	v_fma_f32 v42, v42, v226, v226
	v_fma_f32 v43, v43, v227, v227
	v_fma_f32 v44, v44, v228, v228
	v_fma_f32 v45, v45, v229, v229
	v_add_f32_e32 v38, v38, v218
	v_add_f32_e32 v39, v39, v219
	v_add_f32_e32 v40, v40, v220
	v_add_f32_e32 v41, v41, v221
	v_mul_f32_e32 v38, 0xbfb8aa3b, v38
	v_mul_f32_e32 v39, 0xbfb8aa3b, v39
	v_mul_f32_e32 v40, 0xbfb8aa3b, v40
	v_mul_f32_e32 v41, 0xbfb8aa3b, v41
	v_exp_f32_e32 v38, v38
	v_exp_f32_e32 v39, v39
	v_exp_f32_e32 v40, v40
	v_exp_f32_e32 v41, v41
	s_nop 0
	v_add_f32_e32 v38, 1.0, v38
	v_add_f32_e32 v39, 1.0, v39
	v_add_f32_e32 v40, 1.0, v40
	v_add_f32_e32 v41, 1.0, v41
	v_rcp_f32_e32 v226, v38
	v_rcp_f32_e32 v227, v39
	v_rcp_f32_e32 v228, v40
	v_rcp_f32_e32 v229, v41
	s_nop 0
	v_fma_f32 v38, -v38, v226, 1.0
	v_fma_f32 v39, -v39, v227, 1.0
	v_fma_f32 v40, -v40, v228, 1.0
	v_fma_f32 v41, -v41, v229, 1.0
	v_fma_f32 v38, v38, v226, v226
	v_fma_f32 v39, v39, v227, v227
	v_fma_f32 v40, v40, v228, v228
	v_fma_f32 v41, v41, v229, v229
	v_add_f32_e32 v34, v34, v222
	v_add_f32_e32 v35, v35, v223
	v_add_f32_e32 v36, v36, v224
	v_add_f32_e32 v37, v37, v225
	v_mul_f32_e32 v34, 0xbfb8aa3b, v34
	v_mul_f32_e32 v35, 0xbfb8aa3b, v35
	v_mul_f32_e32 v36, 0xbfb8aa3b, v36
	v_mul_f32_e32 v37, 0xbfb8aa3b, v37
	v_exp_f32_e32 v34, v34
	v_exp_f32_e32 v35, v35
	v_exp_f32_e32 v36, v36
	v_exp_f32_e32 v37, v37
	s_nop 0
	v_add_f32_e32 v34, 1.0, v34
	v_add_f32_e32 v35, 1.0, v35
	v_add_f32_e32 v36, 1.0, v36
	v_add_f32_e32 v37, 1.0, v37
	v_rcp_f32_e32 v226, v34
	v_rcp_f32_e32 v227, v35
	v_rcp_f32_e32 v228, v36
	v_rcp_f32_e32 v229, v37
	s_nop 0
	v_fma_f32 v34, -v34, v226, 1.0
	v_fma_f32 v35, -v35, v227, 1.0
	v_fma_f32 v36, -v36, v228, 1.0
	v_fma_f32 v37, -v37, v229, 1.0
	v_fma_f32 v34, v34, v226, v226
	v_fma_f32 v35, v35, v227, v227
	v_fma_f32 v36, v36, v228, v228
	v_fma_f32 v37, v37, v229, v229
	v_cvt_pk_bf16_f32 v196, v46, v47
	v_cvt_pk_bf16_f32 v197, v48, v49
	v_cvt_pk_bf16_f32 v198, v42, v43
	v_cvt_pk_bf16_f32 v199, v44, v45
	v_cvt_pk_bf16_f32 v200, v38, v39
	v_cvt_pk_bf16_f32 v201, v40, v41
	v_cvt_pk_bf16_f32 v202, v34, v35
	v_cvt_pk_bf16_f32 v203, v36, v37
	v_cmp_gt_i32_e32 vcc, s38, v206
	s_nop 0
	v_permlane16_swap_b32_e32 v196, v198
	v_permlane16_swap_b32_e32 v197, v199
	v_permlane16_swap_b32_e32 v200, v202
	v_permlane16_swap_b32_e32 v201, v203
	s_and_saveexec_b64 s[0:1], vcc
	global_store_dwordx4 v[204:205], v[196:199], off
	global_store_dwordx4 v[204:205], v[200:203], off offset:64
	s_or_b64 exec, exec, s[0:1]
	v_lshl_add_u64 v[204:205], v[204:205], 0, v[208:209]
	v_add_u32_e32 v206, 16, v206
	v_add_f32_e32 v30, v30, v210
	v_add_f32_e32 v31, v31, v211
	v_add_f32_e32 v32, v32, v212
	v_add_f32_e32 v33, v33, v213
	v_mul_f32_e32 v30, 0xbfb8aa3b, v30
	v_mul_f32_e32 v31, 0xbfb8aa3b, v31
	v_mul_f32_e32 v32, 0xbfb8aa3b, v32
	v_mul_f32_e32 v33, 0xbfb8aa3b, v33
	v_exp_f32_e32 v30, v30
	v_exp_f32_e32 v31, v31
	v_exp_f32_e32 v32, v32
	v_exp_f32_e32 v33, v33
	s_nop 0
	v_add_f32_e32 v30, 1.0, v30
	v_add_f32_e32 v31, 1.0, v31
	v_add_f32_e32 v32, 1.0, v32
	v_add_f32_e32 v33, 1.0, v33
	v_rcp_f32_e32 v226, v30
	v_rcp_f32_e32 v227, v31
	v_rcp_f32_e32 v228, v32
	v_rcp_f32_e32 v229, v33
	s_nop 0
	v_fma_f32 v30, -v30, v226, 1.0
	v_fma_f32 v31, -v31, v227, 1.0
	v_fma_f32 v32, -v32, v228, 1.0
	v_fma_f32 v33, -v33, v229, 1.0
	v_fma_f32 v30, v30, v226, v226
	v_fma_f32 v31, v31, v227, v227
	v_fma_f32 v32, v32, v228, v228
	v_fma_f32 v33, v33, v229, v229
	v_add_f32_e32 v26, v26, v214
	v_add_f32_e32 v27, v27, v215
	v_add_f32_e32 v28, v28, v216
	v_add_f32_e32 v29, v29, v217
	v_mul_f32_e32 v26, 0xbfb8aa3b, v26
	v_mul_f32_e32 v27, 0xbfb8aa3b, v27
	v_mul_f32_e32 v28, 0xbfb8aa3b, v28
	v_mul_f32_e32 v29, 0xbfb8aa3b, v29
	v_exp_f32_e32 v26, v26
	v_exp_f32_e32 v27, v27
	v_exp_f32_e32 v28, v28
	v_exp_f32_e32 v29, v29
	s_nop 0
	v_add_f32_e32 v26, 1.0, v26
	v_add_f32_e32 v27, 1.0, v27
	v_add_f32_e32 v28, 1.0, v28
	v_add_f32_e32 v29, 1.0, v29
	v_rcp_f32_e32 v226, v26
	v_rcp_f32_e32 v227, v27
	v_rcp_f32_e32 v228, v28
	v_rcp_f32_e32 v229, v29
	s_nop 0
	v_fma_f32 v26, -v26, v226, 1.0
	v_fma_f32 v27, -v27, v227, 1.0
	v_fma_f32 v28, -v28, v228, 1.0
	v_fma_f32 v29, -v29, v229, 1.0
	v_fma_f32 v26, v26, v226, v226
	v_fma_f32 v27, v27, v227, v227
	v_fma_f32 v28, v28, v228, v228
	v_fma_f32 v29, v29, v229, v229
	v_add_f32_e32 v22, v22, v218
	v_add_f32_e32 v23, v23, v219
	v_add_f32_e32 v24, v24, v220
	v_add_f32_e32 v25, v25, v221
	v_mul_f32_e32 v22, 0xbfb8aa3b, v22
	v_mul_f32_e32 v23, 0xbfb8aa3b, v23
	v_mul_f32_e32 v24, 0xbfb8aa3b, v24
	v_mul_f32_e32 v25, 0xbfb8aa3b, v25
	v_exp_f32_e32 v22, v22
	v_exp_f32_e32 v23, v23
	v_exp_f32_e32 v24, v24
	v_exp_f32_e32 v25, v25
	s_nop 0
	v_add_f32_e32 v22, 1.0, v22
	v_add_f32_e32 v23, 1.0, v23
	v_add_f32_e32 v24, 1.0, v24
	v_add_f32_e32 v25, 1.0, v25
	v_rcp_f32_e32 v226, v22
	v_rcp_f32_e32 v227, v23
	v_rcp_f32_e32 v228, v24
	v_rcp_f32_e32 v229, v25
	s_nop 0
	v_fma_f32 v22, -v22, v226, 1.0
	v_fma_f32 v23, -v23, v227, 1.0
	v_fma_f32 v24, -v24, v228, 1.0
	v_fma_f32 v25, -v25, v229, 1.0
	v_fma_f32 v22, v22, v226, v226
	v_fma_f32 v23, v23, v227, v227
	v_fma_f32 v24, v24, v228, v228
	v_fma_f32 v25, v25, v229, v229
	v_add_f32_e32 v18, v18, v222
	v_add_f32_e32 v19, v19, v223
	v_add_f32_e32 v20, v20, v224
	v_add_f32_e32 v21, v21, v225
	v_mul_f32_e32 v18, 0xbfb8aa3b, v18
	v_mul_f32_e32 v19, 0xbfb8aa3b, v19
	v_mul_f32_e32 v20, 0xbfb8aa3b, v20
	v_mul_f32_e32 v21, 0xbfb8aa3b, v21
	v_exp_f32_e32 v18, v18
	v_exp_f32_e32 v19, v19
	v_exp_f32_e32 v20, v20
	v_exp_f32_e32 v21, v21
	s_nop 0
	v_add_f32_e32 v18, 1.0, v18
	v_add_f32_e32 v19, 1.0, v19
	v_add_f32_e32 v20, 1.0, v20
	v_add_f32_e32 v21, 1.0, v21
	v_rcp_f32_e32 v226, v18
	v_rcp_f32_e32 v227, v19
	v_rcp_f32_e32 v228, v20
	v_rcp_f32_e32 v229, v21
	s_nop 0
	v_fma_f32 v18, -v18, v226, 1.0
	v_fma_f32 v19, -v19, v227, 1.0
	v_fma_f32 v20, -v20, v228, 1.0
	v_fma_f32 v21, -v21, v229, 1.0
	v_fma_f32 v18, v18, v226, v226
	v_fma_f32 v19, v19, v227, v227
	v_fma_f32 v20, v20, v228, v228
	v_fma_f32 v21, v21, v229, v229
	v_cvt_pk_bf16_f32 v196, v30, v31
	v_cvt_pk_bf16_f32 v197, v32, v33
	v_cvt_pk_bf16_f32 v198, v26, v27
	v_cvt_pk_bf16_f32 v199, v28, v29
	v_cvt_pk_bf16_f32 v200, v22, v23
	v_cvt_pk_bf16_f32 v201, v24, v25
	v_cvt_pk_bf16_f32 v202, v18, v19
	v_cvt_pk_bf16_f32 v203, v20, v21
	v_cmp_gt_i32_e32 vcc, s38, v206
	s_nop 0
	v_permlane16_swap_b32_e32 v196, v198
	v_permlane16_swap_b32_e32 v197, v199
	v_permlane16_swap_b32_e32 v200, v202
	v_permlane16_swap_b32_e32 v201, v203
	s_and_saveexec_b64 s[0:1], vcc
	global_store_dwordx4 v[204:205], v[196:199], off
	global_store_dwordx4 v[204:205], v[200:203], off offset:64
	s_or_b64 exec, exec, s[0:1]
	v_lshl_add_u64 v[204:205], v[204:205], 0, v[208:209]
	v_add_u32_e32 v206, 16, v206
	v_add_f32_e32 v14, v14, v210
	v_add_f32_e32 v15, v15, v211
	v_add_f32_e32 v16, v16, v212
	v_add_f32_e32 v17, v17, v213
	v_mul_f32_e32 v14, 0xbfb8aa3b, v14
	v_mul_f32_e32 v15, 0xbfb8aa3b, v15
	v_mul_f32_e32 v16, 0xbfb8aa3b, v16
	v_mul_f32_e32 v17, 0xbfb8aa3b, v17
	v_exp_f32_e32 v14, v14
	v_exp_f32_e32 v15, v15
	v_exp_f32_e32 v16, v16
	v_exp_f32_e32 v17, v17
	s_nop 0
	v_add_f32_e32 v14, 1.0, v14
	v_add_f32_e32 v15, 1.0, v15
	v_add_f32_e32 v16, 1.0, v16
	v_add_f32_e32 v17, 1.0, v17
	v_rcp_f32_e32 v226, v14
	v_rcp_f32_e32 v227, v15
	v_rcp_f32_e32 v228, v16
	v_rcp_f32_e32 v229, v17
	s_nop 0
	v_fma_f32 v14, -v14, v226, 1.0
	v_fma_f32 v15, -v15, v227, 1.0
	v_fma_f32 v16, -v16, v228, 1.0
	v_fma_f32 v17, -v17, v229, 1.0
	v_fma_f32 v14, v14, v226, v226
	v_fma_f32 v15, v15, v227, v227
	v_fma_f32 v16, v16, v228, v228
	v_fma_f32 v17, v17, v229, v229
	v_add_f32_e32 v10, v10, v214
	v_add_f32_e32 v11, v11, v215
	v_add_f32_e32 v12, v12, v216
	v_add_f32_e32 v13, v13, v217
	v_mul_f32_e32 v10, 0xbfb8aa3b, v10
	v_mul_f32_e32 v11, 0xbfb8aa3b, v11
	v_mul_f32_e32 v12, 0xbfb8aa3b, v12
	v_mul_f32_e32 v13, 0xbfb8aa3b, v13
	v_exp_f32_e32 v10, v10
	v_exp_f32_e32 v11, v11
	v_exp_f32_e32 v12, v12
	v_exp_f32_e32 v13, v13
	s_nop 0
	v_add_f32_e32 v10, 1.0, v10
	v_add_f32_e32 v11, 1.0, v11
	v_add_f32_e32 v12, 1.0, v12
	v_add_f32_e32 v13, 1.0, v13
	v_rcp_f32_e32 v226, v10
	v_rcp_f32_e32 v227, v11
	v_rcp_f32_e32 v228, v12
	v_rcp_f32_e32 v229, v13
	s_nop 0
	v_fma_f32 v10, -v10, v226, 1.0
	v_fma_f32 v11, -v11, v227, 1.0
	v_fma_f32 v12, -v12, v228, 1.0
	v_fma_f32 v13, -v13, v229, 1.0
	v_fma_f32 v10, v10, v226, v226
	v_fma_f32 v11, v11, v227, v227
	v_fma_f32 v12, v12, v228, v228
	v_fma_f32 v13, v13, v229, v229
	v_add_f32_e32 v6, v6, v218
	v_add_f32_e32 v7, v7, v219
	v_add_f32_e32 v8, v8, v220
	v_add_f32_e32 v9, v9, v221
	v_mul_f32_e32 v6, 0xbfb8aa3b, v6
	v_mul_f32_e32 v7, 0xbfb8aa3b, v7
	v_mul_f32_e32 v8, 0xbfb8aa3b, v8
	v_mul_f32_e32 v9, 0xbfb8aa3b, v9
	v_exp_f32_e32 v6, v6
	v_exp_f32_e32 v7, v7
	v_exp_f32_e32 v8, v8
	v_exp_f32_e32 v9, v9
	s_nop 0
	v_add_f32_e32 v6, 1.0, v6
	v_add_f32_e32 v7, 1.0, v7
	v_add_f32_e32 v8, 1.0, v8
	v_add_f32_e32 v9, 1.0, v9
	v_rcp_f32_e32 v226, v6
	v_rcp_f32_e32 v227, v7
	v_rcp_f32_e32 v228, v8
	v_rcp_f32_e32 v229, v9
	s_nop 0
	v_fma_f32 v6, -v6, v226, 1.0
	v_fma_f32 v7, -v7, v227, 1.0
	v_fma_f32 v8, -v8, v228, 1.0
	v_fma_f32 v9, -v9, v229, 1.0
	v_fma_f32 v6, v6, v226, v226
	v_fma_f32 v7, v7, v227, v227
	v_fma_f32 v8, v8, v228, v228
	v_fma_f32 v9, v9, v229, v229
	v_add_f32_e32 v2, v2, v222
	v_add_f32_e32 v3, v3, v223
	v_add_f32_e32 v4, v4, v224
	v_add_f32_e32 v5, v5, v225
	v_mul_f32_e32 v2, 0xbfb8aa3b, v2
	v_mul_f32_e32 v3, 0xbfb8aa3b, v3
	v_mul_f32_e32 v4, 0xbfb8aa3b, v4
	v_mul_f32_e32 v5, 0xbfb8aa3b, v5
	v_exp_f32_e32 v2, v2
	v_exp_f32_e32 v3, v3
	v_exp_f32_e32 v4, v4
	v_exp_f32_e32 v5, v5
	s_nop 0
	v_add_f32_e32 v2, 1.0, v2
	v_add_f32_e32 v3, 1.0, v3
	v_add_f32_e32 v4, 1.0, v4
	v_add_f32_e32 v5, 1.0, v5
	v_rcp_f32_e32 v226, v2
	v_rcp_f32_e32 v227, v3
	v_rcp_f32_e32 v228, v4
	v_rcp_f32_e32 v229, v5
	s_nop 0
	v_fma_f32 v2, -v2, v226, 1.0
	v_fma_f32 v3, -v3, v227, 1.0
	v_fma_f32 v4, -v4, v228, 1.0
	v_fma_f32 v5, -v5, v229, 1.0
	v_fma_f32 v2, v2, v226, v226
	v_fma_f32 v3, v3, v227, v227
	v_fma_f32 v4, v4, v228, v228
	v_fma_f32 v5, v5, v229, v229
	v_cvt_pk_bf16_f32 v196, v14, v15
	v_cvt_pk_bf16_f32 v197, v16, v17
	v_cvt_pk_bf16_f32 v198, v10, v11
	v_cvt_pk_bf16_f32 v199, v12, v13
	v_cvt_pk_bf16_f32 v200, v6, v7
	v_cvt_pk_bf16_f32 v201, v8, v9
	v_cvt_pk_bf16_f32 v202, v2, v3
	v_cvt_pk_bf16_f32 v203, v4, v5
	v_cmp_gt_i32_e32 vcc, s38, v206
	s_nop 0
	v_permlane16_swap_b32_e32 v196, v198
	v_permlane16_swap_b32_e32 v197, v199
	v_permlane16_swap_b32_e32 v200, v202
	v_permlane16_swap_b32_e32 v201, v203
	s_and_saveexec_b64 s[0:1], vcc
	global_store_dwordx4 v[204:205], v[196:199], off
	global_store_dwordx4 v[204:205], v[200:203], off offset:64
	s_or_b64 exec, exec, s[0:1]
	s_mov_b64 s[10:11], exec
	s_branch .LBB0_907
